# gla_scan main loop rewritten by hand: 64 steps unrolled, U/DEC loads issued 8 steps ahead through a 16-slot register ring, uniform direction in SGPR strides
# baseline (speedup 1.0000x reference)
.LBB0_724:
	s_and_b64 s[10:11], vcc, exec
	s_mov_b32 s12, 0x8000
	s_mov_b32 s18, 0xffff8000
	s_movk_i32 s14, 0x200
	s_mov_b32 s19, 0xfffffe00
	s_cmp_lg_u64 s[10:11], 0
	s_cselect_b32 s12, s12, s18
	s_cselect_b32 s13, 0, -1
	s_cselect_b32 s14, s14, s19
	s_cselect_b32 s15, 0, -1
	s_cselect_b32 s16, 0, 63
	s_mov_b32 s17, 0
	s_lshl_b32 s18, s16, 15
	s_mov_b32 s19, 0
	v_lshl_add_u64 v[34:35], v[8:9], 0, s[18:19]
	v_lshl_add_u64 v[38:39], v[10:11], 0, s[16:17]
	v_lshlrev_b64 v[38:39], 9, v[38:39]
	v_lshl_add_u64 v[38:39], v[38:39], 0, v[6:7]
	v_mov_b32_e32 v36, v34
	v_mov_b32_e32 v37, v35
	global_load_dwordx4 v[40:43], v[34:35], off
	global_load_dwordx4 v[104:107], v[38:39], off
	global_load_dwordx4 v[170:173], v[38:39], off offset:16
	v_lshl_add_u64 v[34:35], v[34:35], 0, s[12:13]
	v_lshl_add_u64 v[38:39], v[38:39], 0, s[14:15]
	global_load_dwordx4 v[44:47], v[34:35], off
	global_load_dwordx4 v[108:111], v[38:39], off
	global_load_dwordx4 v[174:177], v[38:39], off offset:16
	v_lshl_add_u64 v[34:35], v[34:35], 0, s[12:13]
	v_lshl_add_u64 v[38:39], v[38:39], 0, s[14:15]
	global_load_dwordx4 v[48:51], v[34:35], off
	global_load_dwordx4 v[112:115], v[38:39], off
	global_load_dwordx4 v[178:181], v[38:39], off offset:16
	v_lshl_add_u64 v[34:35], v[34:35], 0, s[12:13]
	v_lshl_add_u64 v[38:39], v[38:39], 0, s[14:15]
	global_load_dwordx4 v[52:55], v[34:35], off
	global_load_dwordx4 v[116:119], v[38:39], off
	global_load_dwordx4 v[186:189], v[38:39], off offset:16
	v_lshl_add_u64 v[34:35], v[34:35], 0, s[12:13]
	v_lshl_add_u64 v[38:39], v[38:39], 0, s[14:15]
	global_load_dwordx4 v[56:59], v[34:35], off
	global_load_dwordx4 v[120:123], v[38:39], off
	global_load_dwordx4 v[190:193], v[38:39], off offset:16
	v_lshl_add_u64 v[34:35], v[34:35], 0, s[12:13]
	v_lshl_add_u64 v[38:39], v[38:39], 0, s[14:15]
	global_load_dwordx4 v[60:63], v[34:35], off
	global_load_dwordx4 v[124:127], v[38:39], off
	global_load_dwordx4 v[194:197], v[38:39], off offset:16
	v_lshl_add_u64 v[34:35], v[34:35], 0, s[12:13]
	v_lshl_add_u64 v[38:39], v[38:39], 0, s[14:15]
	global_load_dwordx4 v[64:67], v[34:35], off
	global_load_dwordx4 v[128:131], v[38:39], off
	global_load_dwordx4 v[198:201], v[38:39], off offset:16
	v_lshl_add_u64 v[34:35], v[34:35], 0, s[12:13]
	v_lshl_add_u64 v[38:39], v[38:39], 0, s[14:15]
	global_load_dwordx4 v[68:71], v[34:35], off
	global_load_dwordx4 v[132:135], v[38:39], off
	global_load_dwordx4 v[202:205], v[38:39], off offset:16
	v_lshl_add_u64 v[34:35], v[34:35], 0, s[12:13]
	v_lshl_add_u64 v[38:39], v[38:39], 0, s[14:15]
	global_load_dwordx4 v[72:75], v[34:35], off
	global_load_dwordx4 v[136:139], v[38:39], off
	global_load_dwordx4 v[206:209], v[38:39], off offset:16
	v_lshl_add_u64 v[34:35], v[34:35], 0, s[12:13]
	v_lshl_add_u64 v[38:39], v[38:39], 0, s[14:15]
	s_waitcnt vmcnt(24)
	v_cvt_pk_bf16_f32 v0, v12, v13
	v_cvt_pk_bf16_f32 v1, v14, v15
	v_cvt_pk_bf16_f32 v2, v16, v17
	v_cvt_pk_bf16_f32 v3, v18, v19
	v_lshlrev_b32_e32 v26, 16, v40
	v_and_b32_e32 v27, 0xffff0000, v40
	v_lshlrev_b32_e32 v28, 16, v41
	v_and_b32_e32 v29, 0xffff0000, v41
	v_lshlrev_b32_e32 v30, 16, v42
	v_and_b32_e32 v31, 0xffff0000, v42
	v_lshlrev_b32_e32 v32, 16, v43
	v_and_b32_e32 v33, 0xffff0000, v43
	global_store_dwordx4 v[36:37], v[0:3], off
	v_lshl_add_u64 v[36:37], v[36:37], 0, s[12:13]
	v_pk_fma_f32 v[12:13], v[12:13], v[104:105], v[26:27]
	v_pk_fma_f32 v[14:15], v[14:15], v[106:107], v[28:29]
	v_pk_fma_f32 v[16:17], v[16:17], v[170:171], v[30:31]
	v_pk_fma_f32 v[18:19], v[18:19], v[172:173], v[32:33]
	global_load_dwordx4 v[76:79], v[34:35], off
	global_load_dwordx4 v[140:143], v[38:39], off
	global_load_dwordx4 v[210:213], v[38:39], off offset:16
	v_lshl_add_u64 v[34:35], v[34:35], 0, s[12:13]
	v_lshl_add_u64 v[38:39], v[38:39], 0, s[14:15]
	s_waitcnt vmcnt(25)
	v_cvt_pk_bf16_f32 v22, v12, v13
	v_cvt_pk_bf16_f32 v23, v14, v15
	v_cvt_pk_bf16_f32 v24, v16, v17
	v_cvt_pk_bf16_f32 v25, v18, v19
	v_lshlrev_b32_e32 v26, 16, v44
	v_and_b32_e32 v27, 0xffff0000, v44
	v_lshlrev_b32_e32 v28, 16, v45
	v_and_b32_e32 v29, 0xffff0000, v45
	v_lshlrev_b32_e32 v30, 16, v46
	v_and_b32_e32 v31, 0xffff0000, v46
	v_lshlrev_b32_e32 v32, 16, v47
	v_and_b32_e32 v33, 0xffff0000, v47
	global_store_dwordx4 v[36:37], v[22:25], off
	v_lshl_add_u64 v[36:37], v[36:37], 0, s[12:13]
	v_pk_fma_f32 v[12:13], v[12:13], v[108:109], v[26:27]
	v_pk_fma_f32 v[14:15], v[14:15], v[110:111], v[28:29]
	v_pk_fma_f32 v[16:17], v[16:17], v[174:175], v[30:31]
	v_pk_fma_f32 v[18:19], v[18:19], v[176:177], v[32:33]
	global_load_dwordx4 v[80:83], v[34:35], off
	global_load_dwordx4 v[146:149], v[38:39], off
	global_load_dwordx4 v[214:217], v[38:39], off offset:16
	v_lshl_add_u64 v[34:35], v[34:35], 0, s[12:13]
	v_lshl_add_u64 v[38:39], v[38:39], 0, s[14:15]
	s_waitcnt vmcnt(26)
	v_cvt_pk_bf16_f32 v0, v12, v13
	v_cvt_pk_bf16_f32 v1, v14, v15
	v_cvt_pk_bf16_f32 v2, v16, v17
	v_cvt_pk_bf16_f32 v3, v18, v19
	v_lshlrev_b32_e32 v26, 16, v48
	v_and_b32_e32 v27, 0xffff0000, v48
	v_lshlrev_b32_e32 v28, 16, v49
	v_and_b32_e32 v29, 0xffff0000, v49
	v_lshlrev_b32_e32 v30, 16, v50
	v_and_b32_e32 v31, 0xffff0000, v50
	v_lshlrev_b32_e32 v32, 16, v51
	v_and_b32_e32 v33, 0xffff0000, v51
	global_store_dwordx4 v[36:37], v[0:3], off
	v_lshl_add_u64 v[36:37], v[36:37], 0, s[12:13]
	v_pk_fma_f32 v[12:13], v[12:13], v[112:113], v[26:27]
	v_pk_fma_f32 v[14:15], v[14:15], v[114:115], v[28:29]
	v_pk_fma_f32 v[16:17], v[16:17], v[178:179], v[30:31]
	v_pk_fma_f32 v[18:19], v[18:19], v[180:181], v[32:33]
	global_load_dwordx4 v[84:87], v[34:35], off
	global_load_dwordx4 v[150:153], v[38:39], off
	global_load_dwordx4 v[218:221], v[38:39], off offset:16
	v_lshl_add_u64 v[34:35], v[34:35], 0, s[12:13]
	v_lshl_add_u64 v[38:39], v[38:39], 0, s[14:15]
	s_waitcnt vmcnt(27)
	v_cvt_pk_bf16_f32 v22, v12, v13
	v_cvt_pk_bf16_f32 v23, v14, v15
	v_cvt_pk_bf16_f32 v24, v16, v17
	v_cvt_pk_bf16_f32 v25, v18, v19
	v_lshlrev_b32_e32 v26, 16, v52
	v_and_b32_e32 v27, 0xffff0000, v52
	v_lshlrev_b32_e32 v28, 16, v53
	v_and_b32_e32 v29, 0xffff0000, v53
	v_lshlrev_b32_e32 v30, 16, v54
	v_and_b32_e32 v31, 0xffff0000, v54
	v_lshlrev_b32_e32 v32, 16, v55
	v_and_b32_e32 v33, 0xffff0000, v55
	global_store_dwordx4 v[36:37], v[22:25], off
	v_lshl_add_u64 v[36:37], v[36:37], 0, s[12:13]
	v_pk_fma_f32 v[12:13], v[12:13], v[116:117], v[26:27]
	v_pk_fma_f32 v[14:15], v[14:15], v[118:119], v[28:29]
	v_pk_fma_f32 v[16:17], v[16:17], v[186:187], v[30:31]
	v_pk_fma_f32 v[18:19], v[18:19], v[188:189], v[32:33]
	global_load_dwordx4 v[88:91], v[34:35], off
	global_load_dwordx4 v[154:157], v[38:39], off
	global_load_dwordx4 v[222:225], v[38:39], off offset:16
	v_lshl_add_u64 v[34:35], v[34:35], 0, s[12:13]
	v_lshl_add_u64 v[38:39], v[38:39], 0, s[14:15]
	s_waitcnt vmcnt(28)
	v_cvt_pk_bf16_f32 v0, v12, v13
	v_cvt_pk_bf16_f32 v1, v14, v15
	v_cvt_pk_bf16_f32 v2, v16, v17
	v_cvt_pk_bf16_f32 v3, v18, v19
	v_lshlrev_b32_e32 v26, 16, v56
	v_and_b32_e32 v27, 0xffff0000, v56
	v_lshlrev_b32_e32 v28, 16, v57
	v_and_b32_e32 v29, 0xffff0000, v57
	v_lshlrev_b32_e32 v30, 16, v58
	v_and_b32_e32 v31, 0xffff0000, v58
	v_lshlrev_b32_e32 v32, 16, v59
	v_and_b32_e32 v33, 0xffff0000, v59
	global_store_dwordx4 v[36:37], v[0:3], off
	v_lshl_add_u64 v[36:37], v[36:37], 0, s[12:13]
	v_pk_fma_f32 v[12:13], v[12:13], v[120:121], v[26:27]
	v_pk_fma_f32 v[14:15], v[14:15], v[122:123], v[28:29]
	v_pk_fma_f32 v[16:17], v[16:17], v[190:191], v[30:31]
	v_pk_fma_f32 v[18:19], v[18:19], v[192:193], v[32:33]
	global_load_dwordx4 v[92:95], v[34:35], off
	global_load_dwordx4 v[158:161], v[38:39], off
	global_load_dwordx4 v[226:229], v[38:39], off offset:16
	v_lshl_add_u64 v[34:35], v[34:35], 0, s[12:13]
	v_lshl_add_u64 v[38:39], v[38:39], 0, s[14:15]
	s_waitcnt vmcnt(29)
	v_cvt_pk_bf16_f32 v22, v12, v13
	v_cvt_pk_bf16_f32 v23, v14, v15
	v_cvt_pk_bf16_f32 v24, v16, v17
	v_cvt_pk_bf16_f32 v25, v18, v19
	v_lshlrev_b32_e32 v26, 16, v60
	v_and_b32_e32 v27, 0xffff0000, v60
	v_lshlrev_b32_e32 v28, 16, v61
	v_and_b32_e32 v29, 0xffff0000, v61
	v_lshlrev_b32_e32 v30, 16, v62
	v_and_b32_e32 v31, 0xffff0000, v62
	v_lshlrev_b32_e32 v32, 16, v63
	v_and_b32_e32 v33, 0xffff0000, v63
	global_store_dwordx4 v[36:37], v[22:25], off
	v_lshl_add_u64 v[36:37], v[36:37], 0, s[12:13]
	v_pk_fma_f32 v[12:13], v[12:13], v[124:125], v[26:27]
	v_pk_fma_f32 v[14:15], v[14:15], v[126:127], v[28:29]
	v_pk_fma_f32 v[16:17], v[16:17], v[194:195], v[30:31]
	v_pk_fma_f32 v[18:19], v[18:19], v[196:197], v[32:33]
	global_load_dwordx4 v[96:99], v[34:35], off
	global_load_dwordx4 v[162:165], v[38:39], off
	global_load_dwordx4 v[230:233], v[38:39], off offset:16
	v_lshl_add_u64 v[34:35], v[34:35], 0, s[12:13]
	v_lshl_add_u64 v[38:39], v[38:39], 0, s[14:15]
	s_waitcnt vmcnt(30)
	v_cvt_pk_bf16_f32 v0, v12, v13
	v_cvt_pk_bf16_f32 v1, v14, v15
	v_cvt_pk_bf16_f32 v2, v16, v17
	v_cvt_pk_bf16_f32 v3, v18, v19
	v_lshlrev_b32_e32 v26, 16, v64
	v_and_b32_e32 v27, 0xffff0000, v64
	v_lshlrev_b32_e32 v28, 16, v65
	v_and_b32_e32 v29, 0xffff0000, v65
	v_lshlrev_b32_e32 v30, 16, v66
	v_and_b32_e32 v31, 0xffff0000, v66
	v_lshlrev_b32_e32 v32, 16, v67
	v_and_b32_e32 v33, 0xffff0000, v67
	global_store_dwordx4 v[36:37], v[0:3], off
	v_lshl_add_u64 v[36:37], v[36:37], 0, s[12:13]
	v_pk_fma_f32 v[12:13], v[12:13], v[128:129], v[26:27]
	v_pk_fma_f32 v[14:15], v[14:15], v[130:131], v[28:29]
	v_pk_fma_f32 v[16:17], v[16:17], v[198:199], v[30:31]
	v_pk_fma_f32 v[18:19], v[18:19], v[200:201], v[32:33]
	global_load_dwordx4 v[100:103], v[34:35], off
	global_load_dwordx4 v[166:169], v[38:39], off
	global_load_dwordx4 v[234:237], v[38:39], off offset:16
	v_lshl_add_u64 v[34:35], v[34:35], 0, s[12:13]
	v_lshl_add_u64 v[38:39], v[38:39], 0, s[14:15]
	s_waitcnt vmcnt(31)
	v_cvt_pk_bf16_f32 v22, v12, v13
	v_cvt_pk_bf16_f32 v23, v14, v15
	v_cvt_pk_bf16_f32 v24, v16, v17
	v_cvt_pk_bf16_f32 v25, v18, v19
	v_lshlrev_b32_e32 v26, 16, v68
	v_and_b32_e32 v27, 0xffff0000, v68
	v_lshlrev_b32_e32 v28, 16, v69
	v_and_b32_e32 v29, 0xffff0000, v69
	v_lshlrev_b32_e32 v30, 16, v70
	v_and_b32_e32 v31, 0xffff0000, v70
	v_lshlrev_b32_e32 v32, 16, v71
	v_and_b32_e32 v33, 0xffff0000, v71
	global_store_dwordx4 v[36:37], v[22:25], off
	v_lshl_add_u64 v[36:37], v[36:37], 0, s[12:13]
	v_pk_fma_f32 v[12:13], v[12:13], v[132:133], v[26:27]
	v_pk_fma_f32 v[14:15], v[14:15], v[134:135], v[28:29]
	v_pk_fma_f32 v[16:17], v[16:17], v[202:203], v[30:31]
	v_pk_fma_f32 v[18:19], v[18:19], v[204:205], v[32:33]
	global_load_dwordx4 v[40:43], v[34:35], off
	global_load_dwordx4 v[104:107], v[38:39], off
	global_load_dwordx4 v[170:173], v[38:39], off offset:16
	v_lshl_add_u64 v[34:35], v[34:35], 0, s[12:13]
	v_lshl_add_u64 v[38:39], v[38:39], 0, s[14:15]
	s_waitcnt vmcnt(32)
	v_cvt_pk_bf16_f32 v0, v12, v13
	v_cvt_pk_bf16_f32 v1, v14, v15
	v_cvt_pk_bf16_f32 v2, v16, v17
	v_cvt_pk_bf16_f32 v3, v18, v19
	v_lshlrev_b32_e32 v26, 16, v72
	v_and_b32_e32 v27, 0xffff0000, v72
	v_lshlrev_b32_e32 v28, 16, v73
	v_and_b32_e32 v29, 0xffff0000, v73
	v_lshlrev_b32_e32 v30, 16, v74
	v_and_b32_e32 v31, 0xffff0000, v74
	v_lshlrev_b32_e32 v32, 16, v75
	v_and_b32_e32 v33, 0xffff0000, v75
	global_store_dwordx4 v[36:37], v[0:3], off
	v_lshl_add_u64 v[36:37], v[36:37], 0, s[12:13]
	v_pk_fma_f32 v[12:13], v[12:13], v[136:137], v[26:27]
	v_pk_fma_f32 v[14:15], v[14:15], v[138:139], v[28:29]
	v_pk_fma_f32 v[16:17], v[16:17], v[206:207], v[30:31]
	v_pk_fma_f32 v[18:19], v[18:19], v[208:209], v[32:33]
	global_load_dwordx4 v[44:47], v[34:35], off
	global_load_dwordx4 v[108:111], v[38:39], off
	global_load_dwordx4 v[174:177], v[38:39], off offset:16
	v_lshl_add_u64 v[34:35], v[34:35], 0, s[12:13]
	v_lshl_add_u64 v[38:39], v[38:39], 0, s[14:15]
	s_waitcnt vmcnt(32)
	v_cvt_pk_bf16_f32 v22, v12, v13
	v_cvt_pk_bf16_f32 v23, v14, v15
	v_cvt_pk_bf16_f32 v24, v16, v17
	v_cvt_pk_bf16_f32 v25, v18, v19
	v_lshlrev_b32_e32 v26, 16, v76
	v_and_b32_e32 v27, 0xffff0000, v76
	v_lshlrev_b32_e32 v28, 16, v77
	v_and_b32_e32 v29, 0xffff0000, v77
	v_lshlrev_b32_e32 v30, 16, v78
	v_and_b32_e32 v31, 0xffff0000, v78
	v_lshlrev_b32_e32 v32, 16, v79
	v_and_b32_e32 v33, 0xffff0000, v79
	global_store_dwordx4 v[36:37], v[22:25], off
	v_lshl_add_u64 v[36:37], v[36:37], 0, s[12:13]
	v_pk_fma_f32 v[12:13], v[12:13], v[140:141], v[26:27]
	v_pk_fma_f32 v[14:15], v[14:15], v[142:143], v[28:29]
	v_pk_fma_f32 v[16:17], v[16:17], v[210:211], v[30:31]
	v_pk_fma_f32 v[18:19], v[18:19], v[212:213], v[32:33]
	global_load_dwordx4 v[48:51], v[34:35], off
	global_load_dwordx4 v[112:115], v[38:39], off
	global_load_dwordx4 v[178:181], v[38:39], off offset:16
	v_lshl_add_u64 v[34:35], v[34:35], 0, s[12:13]
	v_lshl_add_u64 v[38:39], v[38:39], 0, s[14:15]
	s_waitcnt vmcnt(32)
	v_cvt_pk_bf16_f32 v0, v12, v13
	v_cvt_pk_bf16_f32 v1, v14, v15
	v_cvt_pk_bf16_f32 v2, v16, v17
	v_cvt_pk_bf16_f32 v3, v18, v19
	v_lshlrev_b32_e32 v26, 16, v80
	v_and_b32_e32 v27, 0xffff0000, v80
	v_lshlrev_b32_e32 v28, 16, v81
	v_and_b32_e32 v29, 0xffff0000, v81
	v_lshlrev_b32_e32 v30, 16, v82
	v_and_b32_e32 v31, 0xffff0000, v82
	v_lshlrev_b32_e32 v32, 16, v83
	v_and_b32_e32 v33, 0xffff0000, v83
	global_store_dwordx4 v[36:37], v[0:3], off
	v_lshl_add_u64 v[36:37], v[36:37], 0, s[12:13]
	v_pk_fma_f32 v[12:13], v[12:13], v[146:147], v[26:27]
	v_pk_fma_f32 v[14:15], v[14:15], v[148:149], v[28:29]
	v_pk_fma_f32 v[16:17], v[16:17], v[214:215], v[30:31]
	v_pk_fma_f32 v[18:19], v[18:19], v[216:217], v[32:33]
	global_load_dwordx4 v[52:55], v[34:35], off
	global_load_dwordx4 v[116:119], v[38:39], off
	global_load_dwordx4 v[186:189], v[38:39], off offset:16
	v_lshl_add_u64 v[34:35], v[34:35], 0, s[12:13]
	v_lshl_add_u64 v[38:39], v[38:39], 0, s[14:15]
	s_waitcnt vmcnt(32)
	v_cvt_pk_bf16_f32 v22, v12, v13
	v_cvt_pk_bf16_f32 v23, v14, v15
	v_cvt_pk_bf16_f32 v24, v16, v17
	v_cvt_pk_bf16_f32 v25, v18, v19
	v_lshlrev_b32_e32 v26, 16, v84
	v_and_b32_e32 v27, 0xffff0000, v84
	v_lshlrev_b32_e32 v28, 16, v85
	v_and_b32_e32 v29, 0xffff0000, v85
	v_lshlrev_b32_e32 v30, 16, v86
	v_and_b32_e32 v31, 0xffff0000, v86
	v_lshlrev_b32_e32 v32, 16, v87
	v_and_b32_e32 v33, 0xffff0000, v87
	global_store_dwordx4 v[36:37], v[22:25], off
	v_lshl_add_u64 v[36:37], v[36:37], 0, s[12:13]
	v_pk_fma_f32 v[12:13], v[12:13], v[150:151], v[26:27]
	v_pk_fma_f32 v[14:15], v[14:15], v[152:153], v[28:29]
	v_pk_fma_f32 v[16:17], v[16:17], v[218:219], v[30:31]
	v_pk_fma_f32 v[18:19], v[18:19], v[220:221], v[32:33]
	global_load_dwordx4 v[56:59], v[34:35], off
	global_load_dwordx4 v[120:123], v[38:39], off
	global_load_dwordx4 v[190:193], v[38:39], off offset:16
	v_lshl_add_u64 v[34:35], v[34:35], 0, s[12:13]
	v_lshl_add_u64 v[38:39], v[38:39], 0, s[14:15]
	s_waitcnt vmcnt(32)
	v_cvt_pk_bf16_f32 v0, v12, v13
	v_cvt_pk_bf16_f32 v1, v14, v15
	v_cvt_pk_bf16_f32 v2, v16, v17
	v_cvt_pk_bf16_f32 v3, v18, v19
	v_lshlrev_b32_e32 v26, 16, v88
	v_and_b32_e32 v27, 0xffff0000, v88
	v_lshlrev_b32_e32 v28, 16, v89
	v_and_b32_e32 v29, 0xffff0000, v89
	v_lshlrev_b32_e32 v30, 16, v90
	v_and_b32_e32 v31, 0xffff0000, v90
	v_lshlrev_b32_e32 v32, 16, v91
	v_and_b32_e32 v33, 0xffff0000, v91
	global_store_dwordx4 v[36:37], v[0:3], off
	v_lshl_add_u64 v[36:37], v[36:37], 0, s[12:13]
	v_pk_fma_f32 v[12:13], v[12:13], v[154:155], v[26:27]
	v_pk_fma_f32 v[14:15], v[14:15], v[156:157], v[28:29]
	v_pk_fma_f32 v[16:17], v[16:17], v[222:223], v[30:31]
	v_pk_fma_f32 v[18:19], v[18:19], v[224:225], v[32:33]
	global_load_dwordx4 v[60:63], v[34:35], off
	global_load_dwordx4 v[124:127], v[38:39], off
	global_load_dwordx4 v[194:197], v[38:39], off offset:16
	v_lshl_add_u64 v[34:35], v[34:35], 0, s[12:13]
	v_lshl_add_u64 v[38:39], v[38:39], 0, s[14:15]
	s_waitcnt vmcnt(32)
	v_cvt_pk_bf16_f32 v22, v12, v13
	v_cvt_pk_bf16_f32 v23, v14, v15
	v_cvt_pk_bf16_f32 v24, v16, v17
	v_cvt_pk_bf16_f32 v25, v18, v19
	v_lshlrev_b32_e32 v26, 16, v92
	v_and_b32_e32 v27, 0xffff0000, v92
	v_lshlrev_b32_e32 v28, 16, v93
	v_and_b32_e32 v29, 0xffff0000, v93
	v_lshlrev_b32_e32 v30, 16, v94
	v_and_b32_e32 v31, 0xffff0000, v94
	v_lshlrev_b32_e32 v32, 16, v95
	v_and_b32_e32 v33, 0xffff0000, v95
	global_store_dwordx4 v[36:37], v[22:25], off
	v_lshl_add_u64 v[36:37], v[36:37], 0, s[12:13]
	v_pk_fma_f32 v[12:13], v[12:13], v[158:159], v[26:27]
	v_pk_fma_f32 v[14:15], v[14:15], v[160:161], v[28:29]
	v_pk_fma_f32 v[16:17], v[16:17], v[226:227], v[30:31]
	v_pk_fma_f32 v[18:19], v[18:19], v[228:229], v[32:33]
	global_load_dwordx4 v[64:67], v[34:35], off
	global_load_dwordx4 v[128:131], v[38:39], off
	global_load_dwordx4 v[198:201], v[38:39], off offset:16
	v_lshl_add_u64 v[34:35], v[34:35], 0, s[12:13]
	v_lshl_add_u64 v[38:39], v[38:39], 0, s[14:15]
	s_waitcnt vmcnt(32)
	v_cvt_pk_bf16_f32 v0, v12, v13
	v_cvt_pk_bf16_f32 v1, v14, v15
	v_cvt_pk_bf16_f32 v2, v16, v17
	v_cvt_pk_bf16_f32 v3, v18, v19
	v_lshlrev_b32_e32 v26, 16, v96
	v_and_b32_e32 v27, 0xffff0000, v96
	v_lshlrev_b32_e32 v28, 16, v97
	v_and_b32_e32 v29, 0xffff0000, v97
	v_lshlrev_b32_e32 v30, 16, v98
	v_and_b32_e32 v31, 0xffff0000, v98
	v_lshlrev_b32_e32 v32, 16, v99
	v_and_b32_e32 v33, 0xffff0000, v99
	global_store_dwordx4 v[36:37], v[0:3], off
	v_lshl_add_u64 v[36:37], v[36:37], 0, s[12:13]
	v_pk_fma_f32 v[12:13], v[12:13], v[162:163], v[26:27]
	v_pk_fma_f32 v[14:15], v[14:15], v[164:165], v[28:29]
	v_pk_fma_f32 v[16:17], v[16:17], v[230:231], v[30:31]
	v_pk_fma_f32 v[18:19], v[18:19], v[232:233], v[32:33]
	global_load_dwordx4 v[68:71], v[34:35], off
	global_load_dwordx4 v[132:135], v[38:39], off
	global_load_dwordx4 v[202:205], v[38:39], off offset:16
	v_lshl_add_u64 v[34:35], v[34:35], 0, s[12:13]
	v_lshl_add_u64 v[38:39], v[38:39], 0, s[14:15]
	s_waitcnt vmcnt(32)
	v_cvt_pk_bf16_f32 v22, v12, v13
	v_cvt_pk_bf16_f32 v23, v14, v15
	v_cvt_pk_bf16_f32 v24, v16, v17
	v_cvt_pk_bf16_f32 v25, v18, v19
	v_lshlrev_b32_e32 v26, 16, v100
	v_and_b32_e32 v27, 0xffff0000, v100
	v_lshlrev_b32_e32 v28, 16, v101
	v_and_b32_e32 v29, 0xffff0000, v101
	v_lshlrev_b32_e32 v30, 16, v102
	v_and_b32_e32 v31, 0xffff0000, v102
	v_lshlrev_b32_e32 v32, 16, v103
	v_and_b32_e32 v33, 0xffff0000, v103
	global_store_dwordx4 v[36:37], v[22:25], off
	v_lshl_add_u64 v[36:37], v[36:37], 0, s[12:13]
	v_pk_fma_f32 v[12:13], v[12:13], v[166:167], v[26:27]
	v_pk_fma_f32 v[14:15], v[14:15], v[168:169], v[28:29]
	v_pk_fma_f32 v[16:17], v[16:17], v[234:235], v[30:31]
	v_pk_fma_f32 v[18:19], v[18:19], v[236:237], v[32:33]
	global_load_dwordx4 v[72:75], v[34:35], off
	global_load_dwordx4 v[136:139], v[38:39], off
	global_load_dwordx4 v[206:209], v[38:39], off offset:16
	v_lshl_add_u64 v[34:35], v[34:35], 0, s[12:13]
	v_lshl_add_u64 v[38:39], v[38:39], 0, s[14:15]
	s_waitcnt vmcnt(32)
	v_cvt_pk_bf16_f32 v0, v12, v13
	v_cvt_pk_bf16_f32 v1, v14, v15
	v_cvt_pk_bf16_f32 v2, v16, v17
	v_cvt_pk_bf16_f32 v3, v18, v19
	v_lshlrev_b32_e32 v26, 16, v40
	v_and_b32_e32 v27, 0xffff0000, v40
	v_lshlrev_b32_e32 v28, 16, v41
	v_and_b32_e32 v29, 0xffff0000, v41
	v_lshlrev_b32_e32 v30, 16, v42
	v_and_b32_e32 v31, 0xffff0000, v42
	v_lshlrev_b32_e32 v32, 16, v43
	v_and_b32_e32 v33, 0xffff0000, v43
	global_store_dwordx4 v[36:37], v[0:3], off
	v_lshl_add_u64 v[36:37], v[36:37], 0, s[12:13]
	v_pk_fma_f32 v[12:13], v[12:13], v[104:105], v[26:27]
	v_pk_fma_f32 v[14:15], v[14:15], v[106:107], v[28:29]
	v_pk_fma_f32 v[16:17], v[16:17], v[170:171], v[30:31]
	v_pk_fma_f32 v[18:19], v[18:19], v[172:173], v[32:33]
	global_load_dwordx4 v[76:79], v[34:35], off
	global_load_dwordx4 v[140:143], v[38:39], off
	global_load_dwordx4 v[210:213], v[38:39], off offset:16
	v_lshl_add_u64 v[34:35], v[34:35], 0, s[12:13]
	v_lshl_add_u64 v[38:39], v[38:39], 0, s[14:15]
	s_waitcnt vmcnt(32)
	v_cvt_pk_bf16_f32 v22, v12, v13
	v_cvt_pk_bf16_f32 v23, v14, v15
	v_cvt_pk_bf16_f32 v24, v16, v17
	v_cvt_pk_bf16_f32 v25, v18, v19
	v_lshlrev_b32_e32 v26, 16, v44
	v_and_b32_e32 v27, 0xffff0000, v44
	v_lshlrev_b32_e32 v28, 16, v45
	v_and_b32_e32 v29, 0xffff0000, v45
	v_lshlrev_b32_e32 v30, 16, v46
	v_and_b32_e32 v31, 0xffff0000, v46
	v_lshlrev_b32_e32 v32, 16, v47
	v_and_b32_e32 v33, 0xffff0000, v47
	global_store_dwordx4 v[36:37], v[22:25], off
	v_lshl_add_u64 v[36:37], v[36:37], 0, s[12:13]
	v_pk_fma_f32 v[12:13], v[12:13], v[108:109], v[26:27]
	v_pk_fma_f32 v[14:15], v[14:15], v[110:111], v[28:29]
	v_pk_fma_f32 v[16:17], v[16:17], v[174:175], v[30:31]
	v_pk_fma_f32 v[18:19], v[18:19], v[176:177], v[32:33]
	global_load_dwordx4 v[80:83], v[34:35], off
	global_load_dwordx4 v[146:149], v[38:39], off
	global_load_dwordx4 v[214:217], v[38:39], off offset:16
	v_lshl_add_u64 v[34:35], v[34:35], 0, s[12:13]
	v_lshl_add_u64 v[38:39], v[38:39], 0, s[14:15]
	s_waitcnt vmcnt(32)
	v_cvt_pk_bf16_f32 v0, v12, v13
	v_cvt_pk_bf16_f32 v1, v14, v15
	v_cvt_pk_bf16_f32 v2, v16, v17
	v_cvt_pk_bf16_f32 v3, v18, v19
	v_lshlrev_b32_e32 v26, 16, v48
	v_and_b32_e32 v27, 0xffff0000, v48
	v_lshlrev_b32_e32 v28, 16, v49
	v_and_b32_e32 v29, 0xffff0000, v49
	v_lshlrev_b32_e32 v30, 16, v50
	v_and_b32_e32 v31, 0xffff0000, v50
	v_lshlrev_b32_e32 v32, 16, v51
	v_and_b32_e32 v33, 0xffff0000, v51
	global_store_dwordx4 v[36:37], v[0:3], off
	v_lshl_add_u64 v[36:37], v[36:37], 0, s[12:13]
	v_pk_fma_f32 v[12:13], v[12:13], v[112:113], v[26:27]
	v_pk_fma_f32 v[14:15], v[14:15], v[114:115], v[28:29]
	v_pk_fma_f32 v[16:17], v[16:17], v[178:179], v[30:31]
	v_pk_fma_f32 v[18:19], v[18:19], v[180:181], v[32:33]
	global_load_dwordx4 v[84:87], v[34:35], off
	global_load_dwordx4 v[150:153], v[38:39], off
	global_load_dwordx4 v[218:221], v[38:39], off offset:16
	v_lshl_add_u64 v[34:35], v[34:35], 0, s[12:13]
	v_lshl_add_u64 v[38:39], v[38:39], 0, s[14:15]
	s_waitcnt vmcnt(32)
	v_cvt_pk_bf16_f32 v22, v12, v13
	v_cvt_pk_bf16_f32 v23, v14, v15
	v_cvt_pk_bf16_f32 v24, v16, v17
	v_cvt_pk_bf16_f32 v25, v18, v19
	v_lshlrev_b32_e32 v26, 16, v52
	v_and_b32_e32 v27, 0xffff0000, v52
	v_lshlrev_b32_e32 v28, 16, v53
	v_and_b32_e32 v29, 0xffff0000, v53
	v_lshlrev_b32_e32 v30, 16, v54
	v_and_b32_e32 v31, 0xffff0000, v54
	v_lshlrev_b32_e32 v32, 16, v55
	v_and_b32_e32 v33, 0xffff0000, v55
	global_store_dwordx4 v[36:37], v[22:25], off
	v_lshl_add_u64 v[36:37], v[36:37], 0, s[12:13]
	v_pk_fma_f32 v[12:13], v[12:13], v[116:117], v[26:27]
	v_pk_fma_f32 v[14:15], v[14:15], v[118:119], v[28:29]
	v_pk_fma_f32 v[16:17], v[16:17], v[186:187], v[30:31]
	v_pk_fma_f32 v[18:19], v[18:19], v[188:189], v[32:33]
	global_load_dwordx4 v[88:91], v[34:35], off
	global_load_dwordx4 v[154:157], v[38:39], off
	global_load_dwordx4 v[222:225], v[38:39], off offset:16
	v_lshl_add_u64 v[34:35], v[34:35], 0, s[12:13]
	v_lshl_add_u64 v[38:39], v[38:39], 0, s[14:15]
	s_waitcnt vmcnt(32)
	v_cvt_pk_bf16_f32 v0, v12, v13
	v_cvt_pk_bf16_f32 v1, v14, v15
	v_cvt_pk_bf16_f32 v2, v16, v17
	v_cvt_pk_bf16_f32 v3, v18, v19
	v_lshlrev_b32_e32 v26, 16, v56
	v_and_b32_e32 v27, 0xffff0000, v56
	v_lshlrev_b32_e32 v28, 16, v57
	v_and_b32_e32 v29, 0xffff0000, v57
	v_lshlrev_b32_e32 v30, 16, v58
	v_and_b32_e32 v31, 0xffff0000, v58
	v_lshlrev_b32_e32 v32, 16, v59
	v_and_b32_e32 v33, 0xffff0000, v59
	global_store_dwordx4 v[36:37], v[0:3], off
	v_lshl_add_u64 v[36:37], v[36:37], 0, s[12:13]
	v_pk_fma_f32 v[12:13], v[12:13], v[120:121], v[26:27]
	v_pk_fma_f32 v[14:15], v[14:15], v[122:123], v[28:29]
	v_pk_fma_f32 v[16:17], v[16:17], v[190:191], v[30:31]
	v_pk_fma_f32 v[18:19], v[18:19], v[192:193], v[32:33]
	global_load_dwordx4 v[92:95], v[34:35], off
	global_load_dwordx4 v[158:161], v[38:39], off
	global_load_dwordx4 v[226:229], v[38:39], off offset:16
	v_lshl_add_u64 v[34:35], v[34:35], 0, s[12:13]
	v_lshl_add_u64 v[38:39], v[38:39], 0, s[14:15]
	s_waitcnt vmcnt(32)
	v_cvt_pk_bf16_f32 v22, v12, v13
	v_cvt_pk_bf16_f32 v23, v14, v15
	v_cvt_pk_bf16_f32 v24, v16, v17
	v_cvt_pk_bf16_f32 v25, v18, v19
	v_lshlrev_b32_e32 v26, 16, v60
	v_and_b32_e32 v27, 0xffff0000, v60
	v_lshlrev_b32_e32 v28, 16, v61
	v_and_b32_e32 v29, 0xffff0000, v61
	v_lshlrev_b32_e32 v30, 16, v62
	v_and_b32_e32 v31, 0xffff0000, v62
	v_lshlrev_b32_e32 v32, 16, v63
	v_and_b32_e32 v33, 0xffff0000, v63
	global_store_dwordx4 v[36:37], v[22:25], off
	v_lshl_add_u64 v[36:37], v[36:37], 0, s[12:13]
	v_pk_fma_f32 v[12:13], v[12:13], v[124:125], v[26:27]
	v_pk_fma_f32 v[14:15], v[14:15], v[126:127], v[28:29]
	v_pk_fma_f32 v[16:17], v[16:17], v[194:195], v[30:31]
	v_pk_fma_f32 v[18:19], v[18:19], v[196:197], v[32:33]
	global_load_dwordx4 v[96:99], v[34:35], off
	global_load_dwordx4 v[162:165], v[38:39], off
	global_load_dwordx4 v[230:233], v[38:39], off offset:16
	v_lshl_add_u64 v[34:35], v[34:35], 0, s[12:13]
	v_lshl_add_u64 v[38:39], v[38:39], 0, s[14:15]
	s_waitcnt vmcnt(32)
	v_cvt_pk_bf16_f32 v0, v12, v13
	v_cvt_pk_bf16_f32 v1, v14, v15
	v_cvt_pk_bf16_f32 v2, v16, v17
	v_cvt_pk_bf16_f32 v3, v18, v19
	v_lshlrev_b32_e32 v26, 16, v64
	v_and_b32_e32 v27, 0xffff0000, v64
	v_lshlrev_b32_e32 v28, 16, v65
	v_and_b32_e32 v29, 0xffff0000, v65
	v_lshlrev_b32_e32 v30, 16, v66
	v_and_b32_e32 v31, 0xffff0000, v66
	v_lshlrev_b32_e32 v32, 16, v67
	v_and_b32_e32 v33, 0xffff0000, v67
	global_store_dwordx4 v[36:37], v[0:3], off
	v_lshl_add_u64 v[36:37], v[36:37], 0, s[12:13]
	v_pk_fma_f32 v[12:13], v[12:13], v[128:129], v[26:27]
	v_pk_fma_f32 v[14:15], v[14:15], v[130:131], v[28:29]
	v_pk_fma_f32 v[16:17], v[16:17], v[198:199], v[30:31]
	v_pk_fma_f32 v[18:19], v[18:19], v[200:201], v[32:33]
	global_load_dwordx4 v[100:103], v[34:35], off
	global_load_dwordx4 v[166:169], v[38:39], off
	global_load_dwordx4 v[234:237], v[38:39], off offset:16
	v_lshl_add_u64 v[34:35], v[34:35], 0, s[12:13]
	v_lshl_add_u64 v[38:39], v[38:39], 0, s[14:15]
	s_waitcnt vmcnt(32)
	v_cvt_pk_bf16_f32 v22, v12, v13
	v_cvt_pk_bf16_f32 v23, v14, v15
	v_cvt_pk_bf16_f32 v24, v16, v17
	v_cvt_pk_bf16_f32 v25, v18, v19
	v_lshlrev_b32_e32 v26, 16, v68
	v_and_b32_e32 v27, 0xffff0000, v68
	v_lshlrev_b32_e32 v28, 16, v69
	v_and_b32_e32 v29, 0xffff0000, v69
	v_lshlrev_b32_e32 v30, 16, v70
	v_and_b32_e32 v31, 0xffff0000, v70
	v_lshlrev_b32_e32 v32, 16, v71
	v_and_b32_e32 v33, 0xffff0000, v71
	global_store_dwordx4 v[36:37], v[22:25], off
	v_lshl_add_u64 v[36:37], v[36:37], 0, s[12:13]
	v_pk_fma_f32 v[12:13], v[12:13], v[132:133], v[26:27]
	v_pk_fma_f32 v[14:15], v[14:15], v[134:135], v[28:29]
	v_pk_fma_f32 v[16:17], v[16:17], v[202:203], v[30:31]
	v_pk_fma_f32 v[18:19], v[18:19], v[204:205], v[32:33]
	global_load_dwordx4 v[40:43], v[34:35], off
	global_load_dwordx4 v[104:107], v[38:39], off
	global_load_dwordx4 v[170:173], v[38:39], off offset:16
	v_lshl_add_u64 v[34:35], v[34:35], 0, s[12:13]
	v_lshl_add_u64 v[38:39], v[38:39], 0, s[14:15]
	s_waitcnt vmcnt(32)
	v_cvt_pk_bf16_f32 v0, v12, v13
	v_cvt_pk_bf16_f32 v1, v14, v15
	v_cvt_pk_bf16_f32 v2, v16, v17
	v_cvt_pk_bf16_f32 v3, v18, v19
	v_lshlrev_b32_e32 v26, 16, v72
	v_and_b32_e32 v27, 0xffff0000, v72
	v_lshlrev_b32_e32 v28, 16, v73
	v_and_b32_e32 v29, 0xffff0000, v73
	v_lshlrev_b32_e32 v30, 16, v74
	v_and_b32_e32 v31, 0xffff0000, v74
	v_lshlrev_b32_e32 v32, 16, v75
	v_and_b32_e32 v33, 0xffff0000, v75
	global_store_dwordx4 v[36:37], v[0:3], off
	v_lshl_add_u64 v[36:37], v[36:37], 0, s[12:13]
	v_pk_fma_f32 v[12:13], v[12:13], v[136:137], v[26:27]
	v_pk_fma_f32 v[14:15], v[14:15], v[138:139], v[28:29]
	v_pk_fma_f32 v[16:17], v[16:17], v[206:207], v[30:31]
	v_pk_fma_f32 v[18:19], v[18:19], v[208:209], v[32:33]
	global_load_dwordx4 v[44:47], v[34:35], off
	global_load_dwordx4 v[108:111], v[38:39], off
	global_load_dwordx4 v[174:177], v[38:39], off offset:16
	v_lshl_add_u64 v[34:35], v[34:35], 0, s[12:13]
	v_lshl_add_u64 v[38:39], v[38:39], 0, s[14:15]
	s_waitcnt vmcnt(32)
	v_cvt_pk_bf16_f32 v22, v12, v13
	v_cvt_pk_bf16_f32 v23, v14, v15
	v_cvt_pk_bf16_f32 v24, v16, v17
	v_cvt_pk_bf16_f32 v25, v18, v19
	v_lshlrev_b32_e32 v26, 16, v76
	v_and_b32_e32 v27, 0xffff0000, v76
	v_lshlrev_b32_e32 v28, 16, v77
	v_and_b32_e32 v29, 0xffff0000, v77
	v_lshlrev_b32_e32 v30, 16, v78
	v_and_b32_e32 v31, 0xffff0000, v78
	v_lshlrev_b32_e32 v32, 16, v79
	v_and_b32_e32 v33, 0xffff0000, v79
	global_store_dwordx4 v[36:37], v[22:25], off
	v_lshl_add_u64 v[36:37], v[36:37], 0, s[12:13]
	v_pk_fma_f32 v[12:13], v[12:13], v[140:141], v[26:27]
	v_pk_fma_f32 v[14:15], v[14:15], v[142:143], v[28:29]
	v_pk_fma_f32 v[16:17], v[16:17], v[210:211], v[30:31]
	v_pk_fma_f32 v[18:19], v[18:19], v[212:213], v[32:33]
	global_load_dwordx4 v[48:51], v[34:35], off
	global_load_dwordx4 v[112:115], v[38:39], off
	global_load_dwordx4 v[178:181], v[38:39], off offset:16
	v_lshl_add_u64 v[34:35], v[34:35], 0, s[12:13]
	v_lshl_add_u64 v[38:39], v[38:39], 0, s[14:15]
	s_waitcnt vmcnt(32)
	v_cvt_pk_bf16_f32 v0, v12, v13
	v_cvt_pk_bf16_f32 v1, v14, v15
	v_cvt_pk_bf16_f32 v2, v16, v17
	v_cvt_pk_bf16_f32 v3, v18, v19
	v_lshlrev_b32_e32 v26, 16, v80
	v_and_b32_e32 v27, 0xffff0000, v80
	v_lshlrev_b32_e32 v28, 16, v81
	v_and_b32_e32 v29, 0xffff0000, v81
	v_lshlrev_b32_e32 v30, 16, v82
	v_and_b32_e32 v31, 0xffff0000, v82
	v_lshlrev_b32_e32 v32, 16, v83
	v_and_b32_e32 v33, 0xffff0000, v83
	global_store_dwordx4 v[36:37], v[0:3], off
	v_lshl_add_u64 v[36:37], v[36:37], 0, s[12:13]
	v_pk_fma_f32 v[12:13], v[12:13], v[146:147], v[26:27]
	v_pk_fma_f32 v[14:15], v[14:15], v[148:149], v[28:29]
	v_pk_fma_f32 v[16:17], v[16:17], v[214:215], v[30:31]
	v_pk_fma_f32 v[18:19], v[18:19], v[216:217], v[32:33]
	global_load_dwordx4 v[52:55], v[34:35], off
	global_load_dwordx4 v[116:119], v[38:39], off
	global_load_dwordx4 v[186:189], v[38:39], off offset:16
	v_lshl_add_u64 v[34:35], v[34:35], 0, s[12:13]
	v_lshl_add_u64 v[38:39], v[38:39], 0, s[14:15]
	s_waitcnt vmcnt(32)
	v_cvt_pk_bf16_f32 v22, v12, v13
	v_cvt_pk_bf16_f32 v23, v14, v15
	v_cvt_pk_bf16_f32 v24, v16, v17
	v_cvt_pk_bf16_f32 v25, v18, v19
	v_lshlrev_b32_e32 v26, 16, v84
	v_and_b32_e32 v27, 0xffff0000, v84
	v_lshlrev_b32_e32 v28, 16, v85
	v_and_b32_e32 v29, 0xffff0000, v85
	v_lshlrev_b32_e32 v30, 16, v86
	v_and_b32_e32 v31, 0xffff0000, v86
	v_lshlrev_b32_e32 v32, 16, v87
	v_and_b32_e32 v33, 0xffff0000, v87
	global_store_dwordx4 v[36:37], v[22:25], off
	v_lshl_add_u64 v[36:37], v[36:37], 0, s[12:13]
	v_pk_fma_f32 v[12:13], v[12:13], v[150:151], v[26:27]
	v_pk_fma_f32 v[14:15], v[14:15], v[152:153], v[28:29]
	v_pk_fma_f32 v[16:17], v[16:17], v[218:219], v[30:31]
	v_pk_fma_f32 v[18:19], v[18:19], v[220:221], v[32:33]
	global_load_dwordx4 v[56:59], v[34:35], off
	global_load_dwordx4 v[120:123], v[38:39], off
	global_load_dwordx4 v[190:193], v[38:39], off offset:16
	v_lshl_add_u64 v[34:35], v[34:35], 0, s[12:13]
	v_lshl_add_u64 v[38:39], v[38:39], 0, s[14:15]
	s_waitcnt vmcnt(32)
	v_cvt_pk_bf16_f32 v0, v12, v13
	v_cvt_pk_bf16_f32 v1, v14, v15
	v_cvt_pk_bf16_f32 v2, v16, v17
	v_cvt_pk_bf16_f32 v3, v18, v19
	v_lshlrev_b32_e32 v26, 16, v88
	v_and_b32_e32 v27, 0xffff0000, v88
	v_lshlrev_b32_e32 v28, 16, v89
	v_and_b32_e32 v29, 0xffff0000, v89
	v_lshlrev_b32_e32 v30, 16, v90
	v_and_b32_e32 v31, 0xffff0000, v90
	v_lshlrev_b32_e32 v32, 16, v91
	v_and_b32_e32 v33, 0xffff0000, v91
	global_store_dwordx4 v[36:37], v[0:3], off
	v_lshl_add_u64 v[36:37], v[36:37], 0, s[12:13]
	v_pk_fma_f32 v[12:13], v[12:13], v[154:155], v[26:27]
	v_pk_fma_f32 v[14:15], v[14:15], v[156:157], v[28:29]
	v_pk_fma_f32 v[16:17], v[16:17], v[222:223], v[30:31]
	v_pk_fma_f32 v[18:19], v[18:19], v[224:225], v[32:33]
	global_load_dwordx4 v[60:63], v[34:35], off
	global_load_dwordx4 v[124:127], v[38:39], off
	global_load_dwordx4 v[194:197], v[38:39], off offset:16
	v_lshl_add_u64 v[34:35], v[34:35], 0, s[12:13]
	v_lshl_add_u64 v[38:39], v[38:39], 0, s[14:15]
	s_waitcnt vmcnt(32)
	v_cvt_pk_bf16_f32 v22, v12, v13
	v_cvt_pk_bf16_f32 v23, v14, v15
	v_cvt_pk_bf16_f32 v24, v16, v17
	v_cvt_pk_bf16_f32 v25, v18, v19
	v_lshlrev_b32_e32 v26, 16, v92
	v_and_b32_e32 v27, 0xffff0000, v92
	v_lshlrev_b32_e32 v28, 16, v93
	v_and_b32_e32 v29, 0xffff0000, v93
	v_lshlrev_b32_e32 v30, 16, v94
	v_and_b32_e32 v31, 0xffff0000, v94
	v_lshlrev_b32_e32 v32, 16, v95
	v_and_b32_e32 v33, 0xffff0000, v95
	global_store_dwordx4 v[36:37], v[22:25], off
	v_lshl_add_u64 v[36:37], v[36:37], 0, s[12:13]
	v_pk_fma_f32 v[12:13], v[12:13], v[158:159], v[26:27]
	v_pk_fma_f32 v[14:15], v[14:15], v[160:161], v[28:29]
	v_pk_fma_f32 v[16:17], v[16:17], v[226:227], v[30:31]
	v_pk_fma_f32 v[18:19], v[18:19], v[228:229], v[32:33]
	global_load_dwordx4 v[64:67], v[34:35], off
	global_load_dwordx4 v[128:131], v[38:39], off
	global_load_dwordx4 v[198:201], v[38:39], off offset:16
	v_lshl_add_u64 v[34:35], v[34:35], 0, s[12:13]
	v_lshl_add_u64 v[38:39], v[38:39], 0, s[14:15]
	s_waitcnt vmcnt(32)
	v_cvt_pk_bf16_f32 v0, v12, v13
	v_cvt_pk_bf16_f32 v1, v14, v15
	v_cvt_pk_bf16_f32 v2, v16, v17
	v_cvt_pk_bf16_f32 v3, v18, v19
	v_lshlrev_b32_e32 v26, 16, v96
	v_and_b32_e32 v27, 0xffff0000, v96
	v_lshlrev_b32_e32 v28, 16, v97
	v_and_b32_e32 v29, 0xffff0000, v97
	v_lshlrev_b32_e32 v30, 16, v98
	v_and_b32_e32 v31, 0xffff0000, v98
	v_lshlrev_b32_e32 v32, 16, v99
	v_and_b32_e32 v33, 0xffff0000, v99
	global_store_dwordx4 v[36:37], v[0:3], off
	v_lshl_add_u64 v[36:37], v[36:37], 0, s[12:13]
	v_pk_fma_f32 v[12:13], v[12:13], v[162:163], v[26:27]
	v_pk_fma_f32 v[14:15], v[14:15], v[164:165], v[28:29]
	v_pk_fma_f32 v[16:17], v[16:17], v[230:231], v[30:31]
	v_pk_fma_f32 v[18:19], v[18:19], v[232:233], v[32:33]
	global_load_dwordx4 v[68:71], v[34:35], off
	global_load_dwordx4 v[132:135], v[38:39], off
	global_load_dwordx4 v[202:205], v[38:39], off offset:16
	v_lshl_add_u64 v[34:35], v[34:35], 0, s[12:13]
	v_lshl_add_u64 v[38:39], v[38:39], 0, s[14:15]
	s_waitcnt vmcnt(32)
	v_cvt_pk_bf16_f32 v22, v12, v13
	v_cvt_pk_bf16_f32 v23, v14, v15
	v_cvt_pk_bf16_f32 v24, v16, v17
	v_cvt_pk_bf16_f32 v25, v18, v19
	v_lshlrev_b32_e32 v26, 16, v100
	v_and_b32_e32 v27, 0xffff0000, v100
	v_lshlrev_b32_e32 v28, 16, v101
	v_and_b32_e32 v29, 0xffff0000, v101
	v_lshlrev_b32_e32 v30, 16, v102
	v_and_b32_e32 v31, 0xffff0000, v102
	v_lshlrev_b32_e32 v32, 16, v103
	v_and_b32_e32 v33, 0xffff0000, v103
	global_store_dwordx4 v[36:37], v[22:25], off
	v_lshl_add_u64 v[36:37], v[36:37], 0, s[12:13]
	v_pk_fma_f32 v[12:13], v[12:13], v[166:167], v[26:27]
	v_pk_fma_f32 v[14:15], v[14:15], v[168:169], v[28:29]
	v_pk_fma_f32 v[16:17], v[16:17], v[234:235], v[30:31]
	v_pk_fma_f32 v[18:19], v[18:19], v[236:237], v[32:33]
	global_load_dwordx4 v[72:75], v[34:35], off
	global_load_dwordx4 v[136:139], v[38:39], off
	global_load_dwordx4 v[206:209], v[38:39], off offset:16
	v_lshl_add_u64 v[34:35], v[34:35], 0, s[12:13]
	v_lshl_add_u64 v[38:39], v[38:39], 0, s[14:15]
	s_waitcnt vmcnt(32)
	v_cvt_pk_bf16_f32 v0, v12, v13
	v_cvt_pk_bf16_f32 v1, v14, v15
	v_cvt_pk_bf16_f32 v2, v16, v17
	v_cvt_pk_bf16_f32 v3, v18, v19
	v_lshlrev_b32_e32 v26, 16, v40
	v_and_b32_e32 v27, 0xffff0000, v40
	v_lshlrev_b32_e32 v28, 16, v41
	v_and_b32_e32 v29, 0xffff0000, v41
	v_lshlrev_b32_e32 v30, 16, v42
	v_and_b32_e32 v31, 0xffff0000, v42
	v_lshlrev_b32_e32 v32, 16, v43
	v_and_b32_e32 v33, 0xffff0000, v43
	global_store_dwordx4 v[36:37], v[0:3], off
	v_lshl_add_u64 v[36:37], v[36:37], 0, s[12:13]
	v_pk_fma_f32 v[12:13], v[12:13], v[104:105], v[26:27]
	v_pk_fma_f32 v[14:15], v[14:15], v[106:107], v[28:29]
	v_pk_fma_f32 v[16:17], v[16:17], v[170:171], v[30:31]
	v_pk_fma_f32 v[18:19], v[18:19], v[172:173], v[32:33]
	global_load_dwordx4 v[76:79], v[34:35], off
	global_load_dwordx4 v[140:143], v[38:39], off
	global_load_dwordx4 v[210:213], v[38:39], off offset:16
	v_lshl_add_u64 v[34:35], v[34:35], 0, s[12:13]
	v_lshl_add_u64 v[38:39], v[38:39], 0, s[14:15]
	s_waitcnt vmcnt(32)
	v_cvt_pk_bf16_f32 v22, v12, v13
	v_cvt_pk_bf16_f32 v23, v14, v15
	v_cvt_pk_bf16_f32 v24, v16, v17
	v_cvt_pk_bf16_f32 v25, v18, v19
	v_lshlrev_b32_e32 v26, 16, v44
	v_and_b32_e32 v27, 0xffff0000, v44
	v_lshlrev_b32_e32 v28, 16, v45
	v_and_b32_e32 v29, 0xffff0000, v45
	v_lshlrev_b32_e32 v30, 16, v46
	v_and_b32_e32 v31, 0xffff0000, v46
	v_lshlrev_b32_e32 v32, 16, v47
	v_and_b32_e32 v33, 0xffff0000, v47
	global_store_dwordx4 v[36:37], v[22:25], off
	v_lshl_add_u64 v[36:37], v[36:37], 0, s[12:13]
	v_pk_fma_f32 v[12:13], v[12:13], v[108:109], v[26:27]
	v_pk_fma_f32 v[14:15], v[14:15], v[110:111], v[28:29]
	v_pk_fma_f32 v[16:17], v[16:17], v[174:175], v[30:31]
	v_pk_fma_f32 v[18:19], v[18:19], v[176:177], v[32:33]
	global_load_dwordx4 v[80:83], v[34:35], off
	global_load_dwordx4 v[146:149], v[38:39], off
	global_load_dwordx4 v[214:217], v[38:39], off offset:16
	v_lshl_add_u64 v[34:35], v[34:35], 0, s[12:13]
	v_lshl_add_u64 v[38:39], v[38:39], 0, s[14:15]
	s_waitcnt vmcnt(32)
	v_cvt_pk_bf16_f32 v0, v12, v13
	v_cvt_pk_bf16_f32 v1, v14, v15
	v_cvt_pk_bf16_f32 v2, v16, v17
	v_cvt_pk_bf16_f32 v3, v18, v19
	v_lshlrev_b32_e32 v26, 16, v48
	v_and_b32_e32 v27, 0xffff0000, v48
	v_lshlrev_b32_e32 v28, 16, v49
	v_and_b32_e32 v29, 0xffff0000, v49
	v_lshlrev_b32_e32 v30, 16, v50
	v_and_b32_e32 v31, 0xffff0000, v50
	v_lshlrev_b32_e32 v32, 16, v51
	v_and_b32_e32 v33, 0xffff0000, v51
	global_store_dwordx4 v[36:37], v[0:3], off
	v_lshl_add_u64 v[36:37], v[36:37], 0, s[12:13]
	v_pk_fma_f32 v[12:13], v[12:13], v[112:113], v[26:27]
	v_pk_fma_f32 v[14:15], v[14:15], v[114:115], v[28:29]
	v_pk_fma_f32 v[16:17], v[16:17], v[178:179], v[30:31]
	v_pk_fma_f32 v[18:19], v[18:19], v[180:181], v[32:33]
	global_load_dwordx4 v[84:87], v[34:35], off
	global_load_dwordx4 v[150:153], v[38:39], off
	global_load_dwordx4 v[218:221], v[38:39], off offset:16
	v_lshl_add_u64 v[34:35], v[34:35], 0, s[12:13]
	v_lshl_add_u64 v[38:39], v[38:39], 0, s[14:15]
	s_waitcnt vmcnt(32)
	v_cvt_pk_bf16_f32 v22, v12, v13
	v_cvt_pk_bf16_f32 v23, v14, v15
	v_cvt_pk_bf16_f32 v24, v16, v17
	v_cvt_pk_bf16_f32 v25, v18, v19
	v_lshlrev_b32_e32 v26, 16, v52
	v_and_b32_e32 v27, 0xffff0000, v52
	v_lshlrev_b32_e32 v28, 16, v53
	v_and_b32_e32 v29, 0xffff0000, v53
	v_lshlrev_b32_e32 v30, 16, v54
	v_and_b32_e32 v31, 0xffff0000, v54
	v_lshlrev_b32_e32 v32, 16, v55
	v_and_b32_e32 v33, 0xffff0000, v55
	global_store_dwordx4 v[36:37], v[22:25], off
	v_lshl_add_u64 v[36:37], v[36:37], 0, s[12:13]
	v_pk_fma_f32 v[12:13], v[12:13], v[116:117], v[26:27]
	v_pk_fma_f32 v[14:15], v[14:15], v[118:119], v[28:29]
	v_pk_fma_f32 v[16:17], v[16:17], v[186:187], v[30:31]
	v_pk_fma_f32 v[18:19], v[18:19], v[188:189], v[32:33]
	global_load_dwordx4 v[88:91], v[34:35], off
	global_load_dwordx4 v[154:157], v[38:39], off
	global_load_dwordx4 v[222:225], v[38:39], off offset:16
	v_lshl_add_u64 v[34:35], v[34:35], 0, s[12:13]
	v_lshl_add_u64 v[38:39], v[38:39], 0, s[14:15]
	s_waitcnt vmcnt(32)
	v_cvt_pk_bf16_f32 v0, v12, v13
	v_cvt_pk_bf16_f32 v1, v14, v15
	v_cvt_pk_bf16_f32 v2, v16, v17
	v_cvt_pk_bf16_f32 v3, v18, v19
	v_lshlrev_b32_e32 v26, 16, v56
	v_and_b32_e32 v27, 0xffff0000, v56
	v_lshlrev_b32_e32 v28, 16, v57
	v_and_b32_e32 v29, 0xffff0000, v57
	v_lshlrev_b32_e32 v30, 16, v58
	v_and_b32_e32 v31, 0xffff0000, v58
	v_lshlrev_b32_e32 v32, 16, v59
	v_and_b32_e32 v33, 0xffff0000, v59
	global_store_dwordx4 v[36:37], v[0:3], off
	v_lshl_add_u64 v[36:37], v[36:37], 0, s[12:13]
	v_pk_fma_f32 v[12:13], v[12:13], v[120:121], v[26:27]
	v_pk_fma_f32 v[14:15], v[14:15], v[122:123], v[28:29]
	v_pk_fma_f32 v[16:17], v[16:17], v[190:191], v[30:31]
	v_pk_fma_f32 v[18:19], v[18:19], v[192:193], v[32:33]
	global_load_dwordx4 v[92:95], v[34:35], off
	global_load_dwordx4 v[158:161], v[38:39], off
	global_load_dwordx4 v[226:229], v[38:39], off offset:16
	v_lshl_add_u64 v[34:35], v[34:35], 0, s[12:13]
	v_lshl_add_u64 v[38:39], v[38:39], 0, s[14:15]
	s_waitcnt vmcnt(32)
	v_cvt_pk_bf16_f32 v22, v12, v13
	v_cvt_pk_bf16_f32 v23, v14, v15
	v_cvt_pk_bf16_f32 v24, v16, v17
	v_cvt_pk_bf16_f32 v25, v18, v19
	v_lshlrev_b32_e32 v26, 16, v60
	v_and_b32_e32 v27, 0xffff0000, v60
	v_lshlrev_b32_e32 v28, 16, v61
	v_and_b32_e32 v29, 0xffff0000, v61
	v_lshlrev_b32_e32 v30, 16, v62
	v_and_b32_e32 v31, 0xffff0000, v62
	v_lshlrev_b32_e32 v32, 16, v63
	v_and_b32_e32 v33, 0xffff0000, v63
	global_store_dwordx4 v[36:37], v[22:25], off
	v_lshl_add_u64 v[36:37], v[36:37], 0, s[12:13]
	v_pk_fma_f32 v[12:13], v[12:13], v[124:125], v[26:27]
	v_pk_fma_f32 v[14:15], v[14:15], v[126:127], v[28:29]
	v_pk_fma_f32 v[16:17], v[16:17], v[194:195], v[30:31]
	v_pk_fma_f32 v[18:19], v[18:19], v[196:197], v[32:33]
	global_load_dwordx4 v[96:99], v[34:35], off
	global_load_dwordx4 v[162:165], v[38:39], off
	global_load_dwordx4 v[230:233], v[38:39], off offset:16
	v_lshl_add_u64 v[34:35], v[34:35], 0, s[12:13]
	v_lshl_add_u64 v[38:39], v[38:39], 0, s[14:15]
	s_waitcnt vmcnt(32)
	v_cvt_pk_bf16_f32 v0, v12, v13
	v_cvt_pk_bf16_f32 v1, v14, v15
	v_cvt_pk_bf16_f32 v2, v16, v17
	v_cvt_pk_bf16_f32 v3, v18, v19
	v_lshlrev_b32_e32 v26, 16, v64
	v_and_b32_e32 v27, 0xffff0000, v64
	v_lshlrev_b32_e32 v28, 16, v65
	v_and_b32_e32 v29, 0xffff0000, v65
	v_lshlrev_b32_e32 v30, 16, v66
	v_and_b32_e32 v31, 0xffff0000, v66
	v_lshlrev_b32_e32 v32, 16, v67
	v_and_b32_e32 v33, 0xffff0000, v67
	global_store_dwordx4 v[36:37], v[0:3], off
	v_lshl_add_u64 v[36:37], v[36:37], 0, s[12:13]
	v_pk_fma_f32 v[12:13], v[12:13], v[128:129], v[26:27]
	v_pk_fma_f32 v[14:15], v[14:15], v[130:131], v[28:29]
	v_pk_fma_f32 v[16:17], v[16:17], v[198:199], v[30:31]
	v_pk_fma_f32 v[18:19], v[18:19], v[200:201], v[32:33]
	global_load_dwordx4 v[100:103], v[34:35], off
	global_load_dwordx4 v[166:169], v[38:39], off
	global_load_dwordx4 v[234:237], v[38:39], off offset:16
	v_lshl_add_u64 v[34:35], v[34:35], 0, s[12:13]
	v_lshl_add_u64 v[38:39], v[38:39], 0, s[14:15]
	s_waitcnt vmcnt(32)
	v_cvt_pk_bf16_f32 v22, v12, v13
	v_cvt_pk_bf16_f32 v23, v14, v15
	v_cvt_pk_bf16_f32 v24, v16, v17
	v_cvt_pk_bf16_f32 v25, v18, v19
	v_lshlrev_b32_e32 v26, 16, v68
	v_and_b32_e32 v27, 0xffff0000, v68
	v_lshlrev_b32_e32 v28, 16, v69
	v_and_b32_e32 v29, 0xffff0000, v69
	v_lshlrev_b32_e32 v30, 16, v70
	v_and_b32_e32 v31, 0xffff0000, v70
	v_lshlrev_b32_e32 v32, 16, v71
	v_and_b32_e32 v33, 0xffff0000, v71
	global_store_dwordx4 v[36:37], v[22:25], off
	v_lshl_add_u64 v[36:37], v[36:37], 0, s[12:13]
	v_pk_fma_f32 v[12:13], v[12:13], v[132:133], v[26:27]
	v_pk_fma_f32 v[14:15], v[14:15], v[134:135], v[28:29]
	v_pk_fma_f32 v[16:17], v[16:17], v[202:203], v[30:31]
	v_pk_fma_f32 v[18:19], v[18:19], v[204:205], v[32:33]
	global_load_dwordx4 v[40:43], v[34:35], off
	global_load_dwordx4 v[104:107], v[38:39], off
	global_load_dwordx4 v[170:173], v[38:39], off offset:16
	v_lshl_add_u64 v[34:35], v[34:35], 0, s[12:13]
	v_lshl_add_u64 v[38:39], v[38:39], 0, s[14:15]
	s_waitcnt vmcnt(32)
	v_cvt_pk_bf16_f32 v0, v12, v13
	v_cvt_pk_bf16_f32 v1, v14, v15
	v_cvt_pk_bf16_f32 v2, v16, v17
	v_cvt_pk_bf16_f32 v3, v18, v19
	v_lshlrev_b32_e32 v26, 16, v72
	v_and_b32_e32 v27, 0xffff0000, v72
	v_lshlrev_b32_e32 v28, 16, v73
	v_and_b32_e32 v29, 0xffff0000, v73
	v_lshlrev_b32_e32 v30, 16, v74
	v_and_b32_e32 v31, 0xffff0000, v74
	v_lshlrev_b32_e32 v32, 16, v75
	v_and_b32_e32 v33, 0xffff0000, v75
	global_store_dwordx4 v[36:37], v[0:3], off
	v_lshl_add_u64 v[36:37], v[36:37], 0, s[12:13]
	v_pk_fma_f32 v[12:13], v[12:13], v[136:137], v[26:27]
	v_pk_fma_f32 v[14:15], v[14:15], v[138:139], v[28:29]
	v_pk_fma_f32 v[16:17], v[16:17], v[206:207], v[30:31]
	v_pk_fma_f32 v[18:19], v[18:19], v[208:209], v[32:33]
	global_load_dwordx4 v[44:47], v[34:35], off
	global_load_dwordx4 v[108:111], v[38:39], off
	global_load_dwordx4 v[174:177], v[38:39], off offset:16
	v_lshl_add_u64 v[34:35], v[34:35], 0, s[12:13]
	v_lshl_add_u64 v[38:39], v[38:39], 0, s[14:15]
	s_waitcnt vmcnt(32)
	v_cvt_pk_bf16_f32 v22, v12, v13
	v_cvt_pk_bf16_f32 v23, v14, v15
	v_cvt_pk_bf16_f32 v24, v16, v17
	v_cvt_pk_bf16_f32 v25, v18, v19
	v_lshlrev_b32_e32 v26, 16, v76
	v_and_b32_e32 v27, 0xffff0000, v76
	v_lshlrev_b32_e32 v28, 16, v77
	v_and_b32_e32 v29, 0xffff0000, v77
	v_lshlrev_b32_e32 v30, 16, v78
	v_and_b32_e32 v31, 0xffff0000, v78
	v_lshlrev_b32_e32 v32, 16, v79
	v_and_b32_e32 v33, 0xffff0000, v79
	global_store_dwordx4 v[36:37], v[22:25], off
	v_lshl_add_u64 v[36:37], v[36:37], 0, s[12:13]
	v_pk_fma_f32 v[12:13], v[12:13], v[140:141], v[26:27]
	v_pk_fma_f32 v[14:15], v[14:15], v[142:143], v[28:29]
	v_pk_fma_f32 v[16:17], v[16:17], v[210:211], v[30:31]
	v_pk_fma_f32 v[18:19], v[18:19], v[212:213], v[32:33]
	global_load_dwordx4 v[48:51], v[34:35], off
	global_load_dwordx4 v[112:115], v[38:39], off
	global_load_dwordx4 v[178:181], v[38:39], off offset:16
	v_lshl_add_u64 v[34:35], v[34:35], 0, s[12:13]
	v_lshl_add_u64 v[38:39], v[38:39], 0, s[14:15]
	s_waitcnt vmcnt(32)
	v_cvt_pk_bf16_f32 v0, v12, v13
	v_cvt_pk_bf16_f32 v1, v14, v15
	v_cvt_pk_bf16_f32 v2, v16, v17
	v_cvt_pk_bf16_f32 v3, v18, v19
	v_lshlrev_b32_e32 v26, 16, v80
	v_and_b32_e32 v27, 0xffff0000, v80
	v_lshlrev_b32_e32 v28, 16, v81
	v_and_b32_e32 v29, 0xffff0000, v81
	v_lshlrev_b32_e32 v30, 16, v82
	v_and_b32_e32 v31, 0xffff0000, v82
	v_lshlrev_b32_e32 v32, 16, v83
	v_and_b32_e32 v33, 0xffff0000, v83
	global_store_dwordx4 v[36:37], v[0:3], off
	v_lshl_add_u64 v[36:37], v[36:37], 0, s[12:13]
	v_pk_fma_f32 v[12:13], v[12:13], v[146:147], v[26:27]
	v_pk_fma_f32 v[14:15], v[14:15], v[148:149], v[28:29]
	v_pk_fma_f32 v[16:17], v[16:17], v[214:215], v[30:31]
	v_pk_fma_f32 v[18:19], v[18:19], v[216:217], v[32:33]
	global_load_dwordx4 v[52:55], v[34:35], off
	global_load_dwordx4 v[116:119], v[38:39], off
	global_load_dwordx4 v[186:189], v[38:39], off offset:16
	v_lshl_add_u64 v[34:35], v[34:35], 0, s[12:13]
	v_lshl_add_u64 v[38:39], v[38:39], 0, s[14:15]
	s_waitcnt vmcnt(32)
	v_cvt_pk_bf16_f32 v22, v12, v13
	v_cvt_pk_bf16_f32 v23, v14, v15
	v_cvt_pk_bf16_f32 v24, v16, v17
	v_cvt_pk_bf16_f32 v25, v18, v19
	v_lshlrev_b32_e32 v26, 16, v84
	v_and_b32_e32 v27, 0xffff0000, v84
	v_lshlrev_b32_e32 v28, 16, v85
	v_and_b32_e32 v29, 0xffff0000, v85
	v_lshlrev_b32_e32 v30, 16, v86
	v_and_b32_e32 v31, 0xffff0000, v86
	v_lshlrev_b32_e32 v32, 16, v87
	v_and_b32_e32 v33, 0xffff0000, v87
	global_store_dwordx4 v[36:37], v[22:25], off
	v_lshl_add_u64 v[36:37], v[36:37], 0, s[12:13]
	v_pk_fma_f32 v[12:13], v[12:13], v[150:151], v[26:27]
	v_pk_fma_f32 v[14:15], v[14:15], v[152:153], v[28:29]
	v_pk_fma_f32 v[16:17], v[16:17], v[218:219], v[30:31]
	v_pk_fma_f32 v[18:19], v[18:19], v[220:221], v[32:33]
	global_load_dwordx4 v[56:59], v[34:35], off
	global_load_dwordx4 v[120:123], v[38:39], off
	global_load_dwordx4 v[190:193], v[38:39], off offset:16
	v_lshl_add_u64 v[34:35], v[34:35], 0, s[12:13]
	v_lshl_add_u64 v[38:39], v[38:39], 0, s[14:15]
	s_waitcnt vmcnt(32)
	v_cvt_pk_bf16_f32 v0, v12, v13
	v_cvt_pk_bf16_f32 v1, v14, v15
	v_cvt_pk_bf16_f32 v2, v16, v17
	v_cvt_pk_bf16_f32 v3, v18, v19
	v_lshlrev_b32_e32 v26, 16, v88
	v_and_b32_e32 v27, 0xffff0000, v88
	v_lshlrev_b32_e32 v28, 16, v89
	v_and_b32_e32 v29, 0xffff0000, v89
	v_lshlrev_b32_e32 v30, 16, v90
	v_and_b32_e32 v31, 0xffff0000, v90
	v_lshlrev_b32_e32 v32, 16, v91
	v_and_b32_e32 v33, 0xffff0000, v91
	global_store_dwordx4 v[36:37], v[0:3], off
	v_lshl_add_u64 v[36:37], v[36:37], 0, s[12:13]
	v_pk_fma_f32 v[12:13], v[12:13], v[154:155], v[26:27]
	v_pk_fma_f32 v[14:15], v[14:15], v[156:157], v[28:29]
	v_pk_fma_f32 v[16:17], v[16:17], v[222:223], v[30:31]
	v_pk_fma_f32 v[18:19], v[18:19], v[224:225], v[32:33]
	global_load_dwordx4 v[60:63], v[34:35], off
	global_load_dwordx4 v[124:127], v[38:39], off
	global_load_dwordx4 v[194:197], v[38:39], off offset:16
	v_lshl_add_u64 v[34:35], v[34:35], 0, s[12:13]
	v_lshl_add_u64 v[38:39], v[38:39], 0, s[14:15]
	s_waitcnt vmcnt(32)
	v_cvt_pk_bf16_f32 v22, v12, v13
	v_cvt_pk_bf16_f32 v23, v14, v15
	v_cvt_pk_bf16_f32 v24, v16, v17
	v_cvt_pk_bf16_f32 v25, v18, v19
	v_lshlrev_b32_e32 v26, 16, v92
	v_and_b32_e32 v27, 0xffff0000, v92
	v_lshlrev_b32_e32 v28, 16, v93
	v_and_b32_e32 v29, 0xffff0000, v93
	v_lshlrev_b32_e32 v30, 16, v94
	v_and_b32_e32 v31, 0xffff0000, v94
	v_lshlrev_b32_e32 v32, 16, v95
	v_and_b32_e32 v33, 0xffff0000, v95
	global_store_dwordx4 v[36:37], v[22:25], off
	v_lshl_add_u64 v[36:37], v[36:37], 0, s[12:13]
	v_pk_fma_f32 v[12:13], v[12:13], v[158:159], v[26:27]
	v_pk_fma_f32 v[14:15], v[14:15], v[160:161], v[28:29]
	v_pk_fma_f32 v[16:17], v[16:17], v[226:227], v[30:31]
	v_pk_fma_f32 v[18:19], v[18:19], v[228:229], v[32:33]
	global_load_dwordx4 v[64:67], v[34:35], off
	global_load_dwordx4 v[128:131], v[38:39], off
	global_load_dwordx4 v[198:201], v[38:39], off offset:16
	v_lshl_add_u64 v[34:35], v[34:35], 0, s[12:13]
	v_lshl_add_u64 v[38:39], v[38:39], 0, s[14:15]
	s_waitcnt vmcnt(32)
	v_cvt_pk_bf16_f32 v0, v12, v13
	v_cvt_pk_bf16_f32 v1, v14, v15
	v_cvt_pk_bf16_f32 v2, v16, v17
	v_cvt_pk_bf16_f32 v3, v18, v19
	v_lshlrev_b32_e32 v26, 16, v96
	v_and_b32_e32 v27, 0xffff0000, v96
	v_lshlrev_b32_e32 v28, 16, v97
	v_and_b32_e32 v29, 0xffff0000, v97
	v_lshlrev_b32_e32 v30, 16, v98
	v_and_b32_e32 v31, 0xffff0000, v98
	v_lshlrev_b32_e32 v32, 16, v99
	v_and_b32_e32 v33, 0xffff0000, v99
	global_store_dwordx4 v[36:37], v[0:3], off
	v_lshl_add_u64 v[36:37], v[36:37], 0, s[12:13]
	v_pk_fma_f32 v[12:13], v[12:13], v[162:163], v[26:27]
	v_pk_fma_f32 v[14:15], v[14:15], v[164:165], v[28:29]
	v_pk_fma_f32 v[16:17], v[16:17], v[230:231], v[30:31]
	v_pk_fma_f32 v[18:19], v[18:19], v[232:233], v[32:33]
	global_load_dwordx4 v[68:71], v[34:35], off
	global_load_dwordx4 v[132:135], v[38:39], off
	global_load_dwordx4 v[202:205], v[38:39], off offset:16
	v_lshl_add_u64 v[34:35], v[34:35], 0, s[12:13]
	v_lshl_add_u64 v[38:39], v[38:39], 0, s[14:15]
	s_waitcnt vmcnt(32)
	v_cvt_pk_bf16_f32 v22, v12, v13
	v_cvt_pk_bf16_f32 v23, v14, v15
	v_cvt_pk_bf16_f32 v24, v16, v17
	v_cvt_pk_bf16_f32 v25, v18, v19
	v_lshlrev_b32_e32 v26, 16, v100
	v_and_b32_e32 v27, 0xffff0000, v100
	v_lshlrev_b32_e32 v28, 16, v101
	v_and_b32_e32 v29, 0xffff0000, v101
	v_lshlrev_b32_e32 v30, 16, v102
	v_and_b32_e32 v31, 0xffff0000, v102
	v_lshlrev_b32_e32 v32, 16, v103
	v_and_b32_e32 v33, 0xffff0000, v103
	global_store_dwordx4 v[36:37], v[22:25], off
	v_lshl_add_u64 v[36:37], v[36:37], 0, s[12:13]
	v_pk_fma_f32 v[12:13], v[12:13], v[166:167], v[26:27]
	v_pk_fma_f32 v[14:15], v[14:15], v[168:169], v[28:29]
	v_pk_fma_f32 v[16:17], v[16:17], v[234:235], v[30:31]
	v_pk_fma_f32 v[18:19], v[18:19], v[236:237], v[32:33]
	global_load_dwordx4 v[72:75], v[34:35], off
	global_load_dwordx4 v[136:139], v[38:39], off
	global_load_dwordx4 v[206:209], v[38:39], off offset:16
	v_lshl_add_u64 v[34:35], v[34:35], 0, s[12:13]
	v_lshl_add_u64 v[38:39], v[38:39], 0, s[14:15]
	s_waitcnt vmcnt(32)
	v_cvt_pk_bf16_f32 v0, v12, v13
	v_cvt_pk_bf16_f32 v1, v14, v15
	v_cvt_pk_bf16_f32 v2, v16, v17
	v_cvt_pk_bf16_f32 v3, v18, v19
	v_lshlrev_b32_e32 v26, 16, v40
	v_and_b32_e32 v27, 0xffff0000, v40
	v_lshlrev_b32_e32 v28, 16, v41
	v_and_b32_e32 v29, 0xffff0000, v41
	v_lshlrev_b32_e32 v30, 16, v42
	v_and_b32_e32 v31, 0xffff0000, v42
	v_lshlrev_b32_e32 v32, 16, v43
	v_and_b32_e32 v33, 0xffff0000, v43
	global_store_dwordx4 v[36:37], v[0:3], off
	v_lshl_add_u64 v[36:37], v[36:37], 0, s[12:13]
	v_pk_fma_f32 v[12:13], v[12:13], v[104:105], v[26:27]
	v_pk_fma_f32 v[14:15], v[14:15], v[106:107], v[28:29]
	v_pk_fma_f32 v[16:17], v[16:17], v[170:171], v[30:31]
	v_pk_fma_f32 v[18:19], v[18:19], v[172:173], v[32:33]
	global_load_dwordx4 v[76:79], v[34:35], off
	global_load_dwordx4 v[140:143], v[38:39], off
	global_load_dwordx4 v[210:213], v[38:39], off offset:16
	v_lshl_add_u64 v[34:35], v[34:35], 0, s[12:13]
	v_lshl_add_u64 v[38:39], v[38:39], 0, s[14:15]
	s_waitcnt vmcnt(32)
	v_cvt_pk_bf16_f32 v22, v12, v13
	v_cvt_pk_bf16_f32 v23, v14, v15
	v_cvt_pk_bf16_f32 v24, v16, v17
	v_cvt_pk_bf16_f32 v25, v18, v19
	v_lshlrev_b32_e32 v26, 16, v44
	v_and_b32_e32 v27, 0xffff0000, v44
	v_lshlrev_b32_e32 v28, 16, v45
	v_and_b32_e32 v29, 0xffff0000, v45
	v_lshlrev_b32_e32 v30, 16, v46
	v_and_b32_e32 v31, 0xffff0000, v46
	v_lshlrev_b32_e32 v32, 16, v47
	v_and_b32_e32 v33, 0xffff0000, v47
	global_store_dwordx4 v[36:37], v[22:25], off
	v_lshl_add_u64 v[36:37], v[36:37], 0, s[12:13]
	v_pk_fma_f32 v[12:13], v[12:13], v[108:109], v[26:27]
	v_pk_fma_f32 v[14:15], v[14:15], v[110:111], v[28:29]
	v_pk_fma_f32 v[16:17], v[16:17], v[174:175], v[30:31]
	v_pk_fma_f32 v[18:19], v[18:19], v[176:177], v[32:33]
	global_load_dwordx4 v[80:83], v[34:35], off
	global_load_dwordx4 v[146:149], v[38:39], off
	global_load_dwordx4 v[214:217], v[38:39], off offset:16
	v_lshl_add_u64 v[34:35], v[34:35], 0, s[12:13]
	v_lshl_add_u64 v[38:39], v[38:39], 0, s[14:15]
	s_waitcnt vmcnt(32)
	v_cvt_pk_bf16_f32 v0, v12, v13
	v_cvt_pk_bf16_f32 v1, v14, v15
	v_cvt_pk_bf16_f32 v2, v16, v17
	v_cvt_pk_bf16_f32 v3, v18, v19
	v_lshlrev_b32_e32 v26, 16, v48
	v_and_b32_e32 v27, 0xffff0000, v48
	v_lshlrev_b32_e32 v28, 16, v49
	v_and_b32_e32 v29, 0xffff0000, v49
	v_lshlrev_b32_e32 v30, 16, v50
	v_and_b32_e32 v31, 0xffff0000, v50
	v_lshlrev_b32_e32 v32, 16, v51
	v_and_b32_e32 v33, 0xffff0000, v51
	global_store_dwordx4 v[36:37], v[0:3], off
	v_lshl_add_u64 v[36:37], v[36:37], 0, s[12:13]
	v_pk_fma_f32 v[12:13], v[12:13], v[112:113], v[26:27]
	v_pk_fma_f32 v[14:15], v[14:15], v[114:115], v[28:29]
	v_pk_fma_f32 v[16:17], v[16:17], v[178:179], v[30:31]
	v_pk_fma_f32 v[18:19], v[18:19], v[180:181], v[32:33]
	global_load_dwordx4 v[84:87], v[34:35], off
	global_load_dwordx4 v[150:153], v[38:39], off
	global_load_dwordx4 v[218:221], v[38:39], off offset:16
	v_lshl_add_u64 v[34:35], v[34:35], 0, s[12:13]
	v_lshl_add_u64 v[38:39], v[38:39], 0, s[14:15]
	s_waitcnt vmcnt(32)
	v_cvt_pk_bf16_f32 v22, v12, v13
	v_cvt_pk_bf16_f32 v23, v14, v15
	v_cvt_pk_bf16_f32 v24, v16, v17
	v_cvt_pk_bf16_f32 v25, v18, v19
	v_lshlrev_b32_e32 v26, 16, v52
	v_and_b32_e32 v27, 0xffff0000, v52
	v_lshlrev_b32_e32 v28, 16, v53
	v_and_b32_e32 v29, 0xffff0000, v53
	v_lshlrev_b32_e32 v30, 16, v54
	v_and_b32_e32 v31, 0xffff0000, v54
	v_lshlrev_b32_e32 v32, 16, v55
	v_and_b32_e32 v33, 0xffff0000, v55
	global_store_dwordx4 v[36:37], v[22:25], off
	v_lshl_add_u64 v[36:37], v[36:37], 0, s[12:13]
	v_pk_fma_f32 v[12:13], v[12:13], v[116:117], v[26:27]
	v_pk_fma_f32 v[14:15], v[14:15], v[118:119], v[28:29]
	v_pk_fma_f32 v[16:17], v[16:17], v[186:187], v[30:31]
	v_pk_fma_f32 v[18:19], v[18:19], v[188:189], v[32:33]
	global_load_dwordx4 v[88:91], v[34:35], off
	global_load_dwordx4 v[154:157], v[38:39], off
	global_load_dwordx4 v[222:225], v[38:39], off offset:16
	v_lshl_add_u64 v[34:35], v[34:35], 0, s[12:13]
	v_lshl_add_u64 v[38:39], v[38:39], 0, s[14:15]
	s_waitcnt vmcnt(32)
	v_cvt_pk_bf16_f32 v0, v12, v13
	v_cvt_pk_bf16_f32 v1, v14, v15
	v_cvt_pk_bf16_f32 v2, v16, v17
	v_cvt_pk_bf16_f32 v3, v18, v19
	v_lshlrev_b32_e32 v26, 16, v56
	v_and_b32_e32 v27, 0xffff0000, v56
	v_lshlrev_b32_e32 v28, 16, v57
	v_and_b32_e32 v29, 0xffff0000, v57
	v_lshlrev_b32_e32 v30, 16, v58
	v_and_b32_e32 v31, 0xffff0000, v58
	v_lshlrev_b32_e32 v32, 16, v59
	v_and_b32_e32 v33, 0xffff0000, v59
	global_store_dwordx4 v[36:37], v[0:3], off
	v_lshl_add_u64 v[36:37], v[36:37], 0, s[12:13]
	v_pk_fma_f32 v[12:13], v[12:13], v[120:121], v[26:27]
	v_pk_fma_f32 v[14:15], v[14:15], v[122:123], v[28:29]
	v_pk_fma_f32 v[16:17], v[16:17], v[190:191], v[30:31]
	v_pk_fma_f32 v[18:19], v[18:19], v[192:193], v[32:33]
	global_load_dwordx4 v[92:95], v[34:35], off
	global_load_dwordx4 v[158:161], v[38:39], off
	global_load_dwordx4 v[226:229], v[38:39], off offset:16
	v_lshl_add_u64 v[34:35], v[34:35], 0, s[12:13]
	v_lshl_add_u64 v[38:39], v[38:39], 0, s[14:15]
	s_waitcnt vmcnt(32)
	v_cvt_pk_bf16_f32 v22, v12, v13
	v_cvt_pk_bf16_f32 v23, v14, v15
	v_cvt_pk_bf16_f32 v24, v16, v17
	v_cvt_pk_bf16_f32 v25, v18, v19
	v_lshlrev_b32_e32 v26, 16, v60
	v_and_b32_e32 v27, 0xffff0000, v60
	v_lshlrev_b32_e32 v28, 16, v61
	v_and_b32_e32 v29, 0xffff0000, v61
	v_lshlrev_b32_e32 v30, 16, v62
	v_and_b32_e32 v31, 0xffff0000, v62
	v_lshlrev_b32_e32 v32, 16, v63
	v_and_b32_e32 v33, 0xffff0000, v63
	global_store_dwordx4 v[36:37], v[22:25], off
	v_lshl_add_u64 v[36:37], v[36:37], 0, s[12:13]
	v_pk_fma_f32 v[12:13], v[12:13], v[124:125], v[26:27]
	v_pk_fma_f32 v[14:15], v[14:15], v[126:127], v[28:29]
	v_pk_fma_f32 v[16:17], v[16:17], v[194:195], v[30:31]
	v_pk_fma_f32 v[18:19], v[18:19], v[196:197], v[32:33]
	global_load_dwordx4 v[96:99], v[34:35], off
	global_load_dwordx4 v[162:165], v[38:39], off
	global_load_dwordx4 v[230:233], v[38:39], off offset:16
	v_lshl_add_u64 v[34:35], v[34:35], 0, s[12:13]
	v_lshl_add_u64 v[38:39], v[38:39], 0, s[14:15]
	s_waitcnt vmcnt(32)
	v_cvt_pk_bf16_f32 v0, v12, v13
	v_cvt_pk_bf16_f32 v1, v14, v15
	v_cvt_pk_bf16_f32 v2, v16, v17
	v_cvt_pk_bf16_f32 v3, v18, v19
	v_lshlrev_b32_e32 v26, 16, v64
	v_and_b32_e32 v27, 0xffff0000, v64
	v_lshlrev_b32_e32 v28, 16, v65
	v_and_b32_e32 v29, 0xffff0000, v65
	v_lshlrev_b32_e32 v30, 16, v66
	v_and_b32_e32 v31, 0xffff0000, v66
	v_lshlrev_b32_e32 v32, 16, v67
	v_and_b32_e32 v33, 0xffff0000, v67
	global_store_dwordx4 v[36:37], v[0:3], off
	v_lshl_add_u64 v[36:37], v[36:37], 0, s[12:13]
	v_pk_fma_f32 v[12:13], v[12:13], v[128:129], v[26:27]
	v_pk_fma_f32 v[14:15], v[14:15], v[130:131], v[28:29]
	v_pk_fma_f32 v[16:17], v[16:17], v[198:199], v[30:31]
	v_pk_fma_f32 v[18:19], v[18:19], v[200:201], v[32:33]
	global_load_dwordx4 v[100:103], v[34:35], off
	global_load_dwordx4 v[166:169], v[38:39], off
	global_load_dwordx4 v[234:237], v[38:39], off offset:16
	v_lshl_add_u64 v[34:35], v[34:35], 0, s[12:13]
	v_lshl_add_u64 v[38:39], v[38:39], 0, s[14:15]
	s_waitcnt vmcnt(32)
	v_cvt_pk_bf16_f32 v22, v12, v13
	v_cvt_pk_bf16_f32 v23, v14, v15
	v_cvt_pk_bf16_f32 v24, v16, v17
	v_cvt_pk_bf16_f32 v25, v18, v19
	v_lshlrev_b32_e32 v26, 16, v68
	v_and_b32_e32 v27, 0xffff0000, v68
	v_lshlrev_b32_e32 v28, 16, v69
	v_and_b32_e32 v29, 0xffff0000, v69
	v_lshlrev_b32_e32 v30, 16, v70
	v_and_b32_e32 v31, 0xffff0000, v70
	v_lshlrev_b32_e32 v32, 16, v71
	v_and_b32_e32 v33, 0xffff0000, v71
	global_store_dwordx4 v[36:37], v[22:25], off
	v_lshl_add_u64 v[36:37], v[36:37], 0, s[12:13]
	v_pk_fma_f32 v[12:13], v[12:13], v[132:133], v[26:27]
	v_pk_fma_f32 v[14:15], v[14:15], v[134:135], v[28:29]
	v_pk_fma_f32 v[16:17], v[16:17], v[202:203], v[30:31]
	v_pk_fma_f32 v[18:19], v[18:19], v[204:205], v[32:33]
	s_waitcnt vmcnt(29)
	v_cvt_pk_bf16_f32 v0, v12, v13
	v_cvt_pk_bf16_f32 v1, v14, v15
	v_cvt_pk_bf16_f32 v2, v16, v17
	v_cvt_pk_bf16_f32 v3, v18, v19
	v_lshlrev_b32_e32 v26, 16, v72
	v_and_b32_e32 v27, 0xffff0000, v72
	v_lshlrev_b32_e32 v28, 16, v73
	v_and_b32_e32 v29, 0xffff0000, v73
	v_lshlrev_b32_e32 v30, 16, v74
	v_and_b32_e32 v31, 0xffff0000, v74
	v_lshlrev_b32_e32 v32, 16, v75
	v_and_b32_e32 v33, 0xffff0000, v75
	global_store_dwordx4 v[36:37], v[0:3], off
	v_lshl_add_u64 v[36:37], v[36:37], 0, s[12:13]
	v_pk_fma_f32 v[12:13], v[12:13], v[136:137], v[26:27]
	v_pk_fma_f32 v[14:15], v[14:15], v[138:139], v[28:29]
	v_pk_fma_f32 v[16:17], v[16:17], v[206:207], v[30:31]
	v_pk_fma_f32 v[18:19], v[18:19], v[208:209], v[32:33]
	s_waitcnt vmcnt(26)
	v_cvt_pk_bf16_f32 v22, v12, v13
	v_cvt_pk_bf16_f32 v23, v14, v15
	v_cvt_pk_bf16_f32 v24, v16, v17
	v_cvt_pk_bf16_f32 v25, v18, v19
	v_lshlrev_b32_e32 v26, 16, v76
	v_and_b32_e32 v27, 0xffff0000, v76
	v_lshlrev_b32_e32 v28, 16, v77
	v_and_b32_e32 v29, 0xffff0000, v77
	v_lshlrev_b32_e32 v30, 16, v78
	v_and_b32_e32 v31, 0xffff0000, v78
	v_lshlrev_b32_e32 v32, 16, v79
	v_and_b32_e32 v33, 0xffff0000, v79
	global_store_dwordx4 v[36:37], v[22:25], off
	v_lshl_add_u64 v[36:37], v[36:37], 0, s[12:13]
	v_pk_fma_f32 v[12:13], v[12:13], v[140:141], v[26:27]
	v_pk_fma_f32 v[14:15], v[14:15], v[142:143], v[28:29]
	v_pk_fma_f32 v[16:17], v[16:17], v[210:211], v[30:31]
	v_pk_fma_f32 v[18:19], v[18:19], v[212:213], v[32:33]
	s_waitcnt vmcnt(23)
	v_cvt_pk_bf16_f32 v0, v12, v13
	v_cvt_pk_bf16_f32 v1, v14, v15
	v_cvt_pk_bf16_f32 v2, v16, v17
	v_cvt_pk_bf16_f32 v3, v18, v19
	v_lshlrev_b32_e32 v26, 16, v80
	v_and_b32_e32 v27, 0xffff0000, v80
	v_lshlrev_b32_e32 v28, 16, v81
	v_and_b32_e32 v29, 0xffff0000, v81
	v_lshlrev_b32_e32 v30, 16, v82
	v_and_b32_e32 v31, 0xffff0000, v82
	v_lshlrev_b32_e32 v32, 16, v83
	v_and_b32_e32 v33, 0xffff0000, v83
	global_store_dwordx4 v[36:37], v[0:3], off
	v_lshl_add_u64 v[36:37], v[36:37], 0, s[12:13]
	v_pk_fma_f32 v[12:13], v[12:13], v[146:147], v[26:27]
	v_pk_fma_f32 v[14:15], v[14:15], v[148:149], v[28:29]
	v_pk_fma_f32 v[16:17], v[16:17], v[214:215], v[30:31]
	v_pk_fma_f32 v[18:19], v[18:19], v[216:217], v[32:33]
	s_waitcnt vmcnt(20)
	v_cvt_pk_bf16_f32 v22, v12, v13
	v_cvt_pk_bf16_f32 v23, v14, v15
	v_cvt_pk_bf16_f32 v24, v16, v17
	v_cvt_pk_bf16_f32 v25, v18, v19
	v_lshlrev_b32_e32 v26, 16, v84
	v_and_b32_e32 v27, 0xffff0000, v84
	v_lshlrev_b32_e32 v28, 16, v85
	v_and_b32_e32 v29, 0xffff0000, v85
	v_lshlrev_b32_e32 v30, 16, v86
	v_and_b32_e32 v31, 0xffff0000, v86
	v_lshlrev_b32_e32 v32, 16, v87
	v_and_b32_e32 v33, 0xffff0000, v87
	global_store_dwordx4 v[36:37], v[22:25], off
	v_lshl_add_u64 v[36:37], v[36:37], 0, s[12:13]
	v_pk_fma_f32 v[12:13], v[12:13], v[150:151], v[26:27]
	v_pk_fma_f32 v[14:15], v[14:15], v[152:153], v[28:29]
	v_pk_fma_f32 v[16:17], v[16:17], v[218:219], v[30:31]
	v_pk_fma_f32 v[18:19], v[18:19], v[220:221], v[32:33]
	s_waitcnt vmcnt(17)
	v_cvt_pk_bf16_f32 v0, v12, v13
	v_cvt_pk_bf16_f32 v1, v14, v15
	v_cvt_pk_bf16_f32 v2, v16, v17
	v_cvt_pk_bf16_f32 v3, v18, v19
	v_lshlrev_b32_e32 v26, 16, v88
	v_and_b32_e32 v27, 0xffff0000, v88
	v_lshlrev_b32_e32 v28, 16, v89
	v_and_b32_e32 v29, 0xffff0000, v89
	v_lshlrev_b32_e32 v30, 16, v90
	v_and_b32_e32 v31, 0xffff0000, v90
	v_lshlrev_b32_e32 v32, 16, v91
	v_and_b32_e32 v33, 0xffff0000, v91
	global_store_dwordx4 v[36:37], v[0:3], off
	v_lshl_add_u64 v[36:37], v[36:37], 0, s[12:13]
	v_pk_fma_f32 v[12:13], v[12:13], v[154:155], v[26:27]
	v_pk_fma_f32 v[14:15], v[14:15], v[156:157], v[28:29]
	v_pk_fma_f32 v[16:17], v[16:17], v[222:223], v[30:31]
	v_pk_fma_f32 v[18:19], v[18:19], v[224:225], v[32:33]
	s_waitcnt vmcnt(14)
	v_cvt_pk_bf16_f32 v22, v12, v13
	v_cvt_pk_bf16_f32 v23, v14, v15
	v_cvt_pk_bf16_f32 v24, v16, v17
	v_cvt_pk_bf16_f32 v25, v18, v19
	v_lshlrev_b32_e32 v26, 16, v92
	v_and_b32_e32 v27, 0xffff0000, v92
	v_lshlrev_b32_e32 v28, 16, v93
	v_and_b32_e32 v29, 0xffff0000, v93
	v_lshlrev_b32_e32 v30, 16, v94
	v_and_b32_e32 v31, 0xffff0000, v94
	v_lshlrev_b32_e32 v32, 16, v95
	v_and_b32_e32 v33, 0xffff0000, v95
	global_store_dwordx4 v[36:37], v[22:25], off
	v_lshl_add_u64 v[36:37], v[36:37], 0, s[12:13]
	v_pk_fma_f32 v[12:13], v[12:13], v[158:159], v[26:27]
	v_pk_fma_f32 v[14:15], v[14:15], v[160:161], v[28:29]
	v_pk_fma_f32 v[16:17], v[16:17], v[226:227], v[30:31]
	v_pk_fma_f32 v[18:19], v[18:19], v[228:229], v[32:33]
	s_waitcnt vmcnt(11)
	v_cvt_pk_bf16_f32 v0, v12, v13
	v_cvt_pk_bf16_f32 v1, v14, v15
	v_cvt_pk_bf16_f32 v2, v16, v17
	v_cvt_pk_bf16_f32 v3, v18, v19
	v_lshlrev_b32_e32 v26, 16, v96
	v_and_b32_e32 v27, 0xffff0000, v96
	v_lshlrev_b32_e32 v28, 16, v97
	v_and_b32_e32 v29, 0xffff0000, v97
	v_lshlrev_b32_e32 v30, 16, v98
	v_and_b32_e32 v31, 0xffff0000, v98
	v_lshlrev_b32_e32 v32, 16, v99
	v_and_b32_e32 v33, 0xffff0000, v99
	global_store_dwordx4 v[36:37], v[0:3], off
	v_lshl_add_u64 v[36:37], v[36:37], 0, s[12:13]
	v_pk_fma_f32 v[12:13], v[12:13], v[162:163], v[26:27]
	v_pk_fma_f32 v[14:15], v[14:15], v[164:165], v[28:29]
	v_pk_fma_f32 v[16:17], v[16:17], v[230:231], v[30:31]
	v_pk_fma_f32 v[18:19], v[18:19], v[232:233], v[32:33]
	s_waitcnt vmcnt(8)
	v_cvt_pk_bf16_f32 v22, v12, v13
	v_cvt_pk_bf16_f32 v23, v14, v15
	v_cvt_pk_bf16_f32 v24, v16, v17
	v_cvt_pk_bf16_f32 v25, v18, v19
	v_lshlrev_b32_e32 v26, 16, v100
	v_and_b32_e32 v27, 0xffff0000, v100
	v_lshlrev_b32_e32 v28, 16, v101
	v_and_b32_e32 v29, 0xffff0000, v101
	v_lshlrev_b32_e32 v30, 16, v102
	v_and_b32_e32 v31, 0xffff0000, v102
	v_lshlrev_b32_e32 v32, 16, v103
	v_and_b32_e32 v33, 0xffff0000, v103
	global_store_dwordx4 v[36:37], v[22:25], off
	v_lshl_add_u64 v[36:37], v[36:37], 0, s[12:13]
	v_pk_fma_f32 v[12:13], v[12:13], v[166:167], v[26:27]
	v_pk_fma_f32 v[14:15], v[14:15], v[168:169], v[28:29]
	v_pk_fma_f32 v[16:17], v[16:17], v[234:235], v[30:31]
	v_pk_fma_f32 v[18:19], v[18:19], v[236:237], v[32:33]
	v_add_u32_e32 v20, s8, v20
	v_cmp_lt_i32_e32 vcc, s9, v20
	s_or_b64 s[6:7], vcc, s[6:7]
	s_andn2_b64 exec, exec, s[6:7]
	s_cbranch_execnz .LBB0_723
